# GEMM units: redundant first accumulator zeroing (127 v_mov per tile) moved off the main path; GLA barrier B1 removed (SLR written a chunk early); far-branch trampoline
# speedup vs baseline: 1.0136x; 1.0003x over previous
; #define LAS __attribute__((address_space(3)))
;     ...
;         const bool has_next = S.next(ui + 1, nxt);
;         const unsigned rsoff = (unsigned)STAGE_BYTES + (unsigned)(ui & 1) * 1024u;
;         if constexpr (Epi::NEEDS_RS) { if (wid < 4) __builtin_amdgcn_global_load_lds((const unsigned*)(E.rsv + cur.pm * 256 + wid * 64 + lane), (LAS unsigned*)(lds + rsoff + wid * 256), 4, 0, 0); }
;         const char* nA = has_next ? (const char*)g.A + (size_t)nxt.pm * tstepA + (size_t)nxt.pn * APN : cA; const char* nB = has_next ? (const char*)g.Bt + (size_t)nxt.pn * tstepB : cB;
;         for (int t = 0; t < nt; t += 2) {
;             const bool last = (t == nt - 2);
;             const char* a1 = cA + (size_t)(t + 1) * kstep;
;             const char* a2 = last ? nA : cA + (size_t)(t + 2) * kstep; const char* b2 = last ? nB : cB + (size_t)(t + 2) * kstep;
;             const char* a3 = a2 + kstep; const char* b3 = b2 + kstep;
;     ...
; #pragma unroll
;         for (int a = 0; a < 2; ++a)
; #pragma unroll
;             for (int b = 0; b < 2; ++b)
; #pragma unroll
;                 for (int m = 0; m < 4; ++m)
; #pragma unroll
;                     for (int n = 0; n < 2; ++n) acc[a][b][m][n] = (f32x4){0.f, 0.f, 0.f, 0.f};
;         cur = nxt; cA = nA; cB = nB; ++ui;
.LBB0_82:
	s_andn2_b64 vcc, exec, s[24:25]
	s_waitcnt lgkmcnt(0)
	s_cbranch_vccnz .Lzskip_0
	s_add_u32 s14, s4, 0x100
	v_mov_b32_e32 v0, 0
	s_addc_u32 s15, s5, 0
	s_mov_b32 s8, 0
	v_mov_b32_e32 v1, v0
	v_mov_b32_e32 v2, v0
	v_mov_b32_e32 v3, v0
	v_mov_b32_e32 v4, v0
	v_mov_b32_e32 v5, v0
	v_mov_b32_e32 v6, v0
	v_mov_b32_e32 v7, v0
	v_mov_b32_e32 v16, v0
	v_mov_b32_e32 v17, v0
	v_mov_b32_e32 v18, v0
	v_mov_b32_e32 v19, v0
	v_mov_b32_e32 v20, v0
	v_mov_b32_e32 v21, v0
	v_mov_b32_e32 v22, v0
	v_mov_b32_e32 v23, v0
	v_mov_b32_e32 v32, v0
	v_mov_b32_e32 v33, v0
	v_mov_b32_e32 v34, v0
	v_mov_b32_e32 v35, v0
	v_mov_b32_e32 v36, v0
	v_mov_b32_e32 v37, v0
	v_mov_b32_e32 v38, v0
	v_mov_b32_e32 v39, v0
	v_mov_b32_e32 v48, v0
	v_mov_b32_e32 v49, v0
	v_mov_b32_e32 v50, v0
	v_mov_b32_e32 v51, v0
	v_mov_b32_e32 v52, v0
	v_mov_b32_e32 v53, v0
	v_mov_b32_e32 v54, v0
	v_mov_b32_e32 v55, v0
	v_mov_b32_e32 v8, v0
	v_mov_b32_e32 v9, v0
	v_mov_b32_e32 v10, v0
	v_mov_b32_e32 v11, v0
	v_mov_b32_e32 v12, v0
	v_mov_b32_e32 v13, v0
	v_mov_b32_e32 v14, v0
	v_mov_b32_e32 v15, v0
	v_mov_b32_e32 v24, v0
	v_mov_b32_e32 v25, v0
	v_mov_b32_e32 v26, v0
	v_mov_b32_e32 v27, v0
	v_mov_b32_e32 v28, v0
	v_mov_b32_e32 v29, v0
	v_mov_b32_e32 v30, v0
	v_mov_b32_e32 v31, v0
	v_mov_b32_e32 v40, v0
	v_mov_b32_e32 v41, v0
	v_mov_b32_e32 v42, v0
	v_mov_b32_e32 v43, v0
	v_mov_b32_e32 v44, v0
	v_mov_b32_e32 v45, v0
	v_mov_b32_e32 v46, v0
	v_mov_b32_e32 v47, v0
	v_mov_b32_e32 v56, v0
	v_mov_b32_e32 v57, v0
	v_mov_b32_e32 v58, v0
	v_mov_b32_e32 v59, v0
	v_mov_b32_e32 v60, v0
	v_mov_b32_e32 v61, v0
	v_mov_b32_e32 v62, v0
	v_mov_b32_e32 v63, v0
	v_mov_b32_e32 v64, v0
	v_mov_b32_e32 v65, v0
	v_mov_b32_e32 v66, v0
	v_mov_b32_e32 v67, v0
	v_mov_b32_e32 v68, v0
	v_mov_b32_e32 v69, v0
	v_mov_b32_e32 v70, v0
	v_mov_b32_e32 v71, v0
	v_mov_b32_e32 v80, v0
	v_mov_b32_e32 v81, v0
	v_mov_b32_e32 v82, v0
	v_mov_b32_e32 v83, v0
	v_mov_b32_e32 v84, v0
	v_mov_b32_e32 v85, v0
	v_mov_b32_e32 v86, v0
	v_mov_b32_e32 v87, v0
	v_mov_b32_e32 v96, v0
	v_mov_b32_e32 v97, v0
	v_mov_b32_e32 v98, v0
	v_mov_b32_e32 v99, v0
	v_mov_b32_e32 v100, v0
	v_mov_b32_e32 v101, v0
	v_mov_b32_e32 v102, v0
	v_mov_b32_e32 v103, v0
	v_mov_b32_e32 v112, v0
	v_mov_b32_e32 v113, v0
	v_mov_b32_e32 v114, v0
	v_mov_b32_e32 v115, v0
	v_mov_b32_e32 v116, v0
	v_mov_b32_e32 v117, v0
	v_mov_b32_e32 v118, v0
	v_mov_b32_e32 v119, v0
	v_mov_b32_e32 v72, v0
	v_mov_b32_e32 v73, v0
	v_mov_b32_e32 v74, v0
	v_mov_b32_e32 v75, v0
	v_mov_b32_e32 v76, v0
	v_mov_b32_e32 v77, v0
	v_mov_b32_e32 v78, v0
	v_mov_b32_e32 v79, v0
	v_mov_b32_e32 v88, v0
	v_mov_b32_e32 v89, v0
	v_mov_b32_e32 v90, v0
	v_mov_b32_e32 v91, v0
	v_mov_b32_e32 v92, v0
	v_mov_b32_e32 v93, v0
	v_mov_b32_e32 v94, v0
	v_mov_b32_e32 v95, v0
	v_mov_b32_e32 v104, v0
	v_mov_b32_e32 v105, v0
	v_mov_b32_e32 v106, v0
	v_mov_b32_e32 v107, v0
	v_mov_b32_e32 v108, v0
	v_mov_b32_e32 v109, v0
	v_mov_b32_e32 v110, v0
	v_mov_b32_e32 v111, v0
	v_mov_b32_e32 v120, v0
	v_mov_b32_e32 v121, v0
	v_mov_b32_e32 v122, v0
	v_mov_b32_e32 v123, v0
	v_mov_b32_e32 v124, v0
	v_mov_b32_e32 v125, v0
	v_mov_b32_e32 v126, v0
	v_mov_b32_e32 v127, v0
	s_mov_b64 s[58:59], 0x80

;     ...
; #pragma unroll
;         for (int a = 0; a < 2; ++a)
; #pragma unroll
;             for (int b = 0; b < 2; ++b)
; #pragma unroll
;                 for (int m = 0; m < 4; ++m)
; #pragma unroll
;                     for (int n = 0; n < 2; ++n) acc[a][b][m][n] = (f32x4){0.f, 0.f, 0.f, 0.f};
.Lzskip_0:
	v_mov_b32_e32 v127, 0
	v_mov_b32_e32 v126, v127
	v_mov_b32_e32 v125, v127
	v_mov_b32_e32 v124, v127
	v_mov_b32_e32 v123, v127
	v_mov_b32_e32 v122, v127
	v_mov_b32_e32 v121, v127
	v_mov_b32_e32 v120, v127
	v_mov_b32_e32 v111, v127
	v_mov_b32_e32 v110, v127
	v_mov_b32_e32 v109, v127
	v_mov_b32_e32 v108, v127
	v_mov_b32_e32 v107, v127
	v_mov_b32_e32 v106, v127
	v_mov_b32_e32 v105, v127
	v_mov_b32_e32 v104, v127
	v_mov_b32_e32 v95, v127
	v_mov_b32_e32 v94, v127
	v_mov_b32_e32 v93, v127
	v_mov_b32_e32 v92, v127
	v_mov_b32_e32 v91, v127
	v_mov_b32_e32 v90, v127
	v_mov_b32_e32 v89, v127
	v_mov_b32_e32 v88, v127
	v_mov_b32_e32 v79, v127
	v_mov_b32_e32 v78, v127
	v_mov_b32_e32 v77, v127
	v_mov_b32_e32 v76, v127
	v_mov_b32_e32 v75, v127
	v_mov_b32_e32 v74, v127
	v_mov_b32_e32 v73, v127
	v_mov_b32_e32 v72, v127
	v_mov_b32_e32 v119, v127
	v_mov_b32_e32 v118, v127
	v_mov_b32_e32 v117, v127
	v_mov_b32_e32 v116, v127
	v_mov_b32_e32 v115, v127
	v_mov_b32_e32 v114, v127
	v_mov_b32_e32 v113, v127
	v_mov_b32_e32 v112, v127
	v_mov_b32_e32 v103, v127
	v_mov_b32_e32 v102, v127
	v_mov_b32_e32 v101, v127
	v_mov_b32_e32 v100, v127
	v_mov_b32_e32 v99, v127
	v_mov_b32_e32 v98, v127
	v_mov_b32_e32 v97, v127
	v_mov_b32_e32 v96, v127
	v_mov_b32_e32 v87, v127
	v_mov_b32_e32 v86, v127
	v_mov_b32_e32 v85, v127
	v_mov_b32_e32 v84, v127
	v_mov_b32_e32 v83, v127
	v_mov_b32_e32 v82, v127
	v_mov_b32_e32 v81, v127
	v_mov_b32_e32 v80, v127
	v_mov_b32_e32 v71, v127
	v_mov_b32_e32 v70, v127
	v_mov_b32_e32 v69, v127
	v_mov_b32_e32 v68, v127
	v_mov_b32_e32 v67, v127
	v_mov_b32_e32 v66, v127
	v_mov_b32_e32 v65, v127
	v_mov_b32_e32 v64, v127
	v_mov_b32_e32 v63, v127
	v_mov_b32_e32 v62, v127
	v_mov_b32_e32 v61, v127
	v_mov_b32_e32 v60, v127
	v_mov_b32_e32 v59, v127
	v_mov_b32_e32 v58, v127
	v_mov_b32_e32 v57, v127
	v_mov_b32_e32 v56, v127
	v_mov_b32_e32 v47, v127
	v_mov_b32_e32 v46, v127
	v_mov_b32_e32 v45, v127
	v_mov_b32_e32 v44, v127
	v_mov_b32_e32 v43, v127
	v_mov_b32_e32 v42, v127
	v_mov_b32_e32 v41, v127
	v_mov_b32_e32 v40, v127
	v_mov_b32_e32 v31, v127
	v_mov_b32_e32 v30, v127
	v_mov_b32_e32 v29, v127
	v_mov_b32_e32 v28, v127
	v_mov_b32_e32 v27, v127
	v_mov_b32_e32 v26, v127
	v_mov_b32_e32 v25, v127
	v_mov_b32_e32 v24, v127
	v_mov_b32_e32 v15, v127
	v_mov_b32_e32 v14, v127
	v_mov_b32_e32 v13, v127
	v_mov_b32_e32 v12, v127
	v_mov_b32_e32 v11, v127
	v_mov_b32_e32 v10, v127
	v_mov_b32_e32 v9, v127
	v_mov_b32_e32 v8, v127
	v_mov_b32_e32 v55, v127
	v_mov_b32_e32 v54, v127
	v_mov_b32_e32 v53, v127
	v_mov_b32_e32 v52, v127
	v_mov_b32_e32 v51, v127
	v_mov_b32_e32 v50, v127
	v_mov_b32_e32 v49, v127
	v_mov_b32_e32 v48, v127
	v_mov_b32_e32 v39, v127
	v_mov_b32_e32 v38, v127
	v_mov_b32_e32 v37, v127
	v_mov_b32_e32 v36, v127
	v_mov_b32_e32 v35, v127
	v_mov_b32_e32 v34, v127
	v_mov_b32_e32 v33, v127
	v_mov_b32_e32 v32, v127
	v_mov_b32_e32 v23, v127
	v_mov_b32_e32 v22, v127
	v_mov_b32_e32 v21, v127
	v_mov_b32_e32 v20, v127
	v_mov_b32_e32 v19, v127
	v_mov_b32_e32 v18, v127
	v_mov_b32_e32 v17, v127
	v_mov_b32_e32 v16, v127
	v_mov_b32_e32 v7, v127
	v_mov_b32_e32 v6, v127
	v_mov_b32_e32 v5, v127
	v_mov_b32_e32 v4, v127
	v_mov_b32_e32 v3, v127
	v_mov_b32_e32 v2, v127
	v_mov_b32_e32 v1, v127
	v_mov_b32_e32 v0, v127
	s_branch .LBB0_85

; #define LAS __attribute__((address_space(3)))
;     ...
;         const bool has_next = S.next(ui + 1, nxt);
;         const unsigned rsoff = (unsigned)STAGE_BYTES + (unsigned)(ui & 1) * 1024u;
;         if constexpr (Epi::NEEDS_RS) { if (wid < 4) __builtin_amdgcn_global_load_lds((const unsigned*)(E.rsv + cur.pm * 256 + wid * 64 + lane), (LAS unsigned*)(lds + rsoff + wid * 256), 4, 0, 0); }
;         const char* nA = has_next ? (const char*)g.A + (size_t)nxt.pm * tstepA + (size_t)nxt.pn * APN : cA; const char* nB = has_next ? (const char*)g.Bt + (size_t)nxt.pn * tstepB : cB;
;         for (int t = 0; t < nt; t += 2) {
;             const bool last = (t == nt - 2);
;             const char* a1 = cA + (size_t)(t + 1) * kstep;
;             const char* a2 = last ? nA : cA + (size_t)(t + 2) * kstep; const char* b2 = last ? nB : cB + (size_t)(t + 2) * kstep;
;             const char* a3 = a2 + kstep; const char* b3 = b2 + kstep;
;     ...
; #pragma unroll
;         for (int a = 0; a < 2; ++a)
; #pragma unroll
;             for (int b = 0; b < 2; ++b)
; #pragma unroll
;                 for (int m = 0; m < 4; ++m)
; #pragma unroll
;                     for (int n = 0; n < 2; ++n) acc[a][b][m][n] = (f32x4){0.f, 0.f, 0.f, 0.f};
;         cur = nxt; cA = nA; cB = nB; ++ui;
.LBB0_131:
	s_andn2_b64 vcc, exec, s[28:29]
	s_cbranch_vccnz .Lzskip_1
	s_add_u32 s7, s2, 0x100
	v_mov_b32_e32 v0, 0
	v_mov_b64_e32 v[212:213], 0x77f
	v_mov_b64_e32 v[154:155], 0x780
	s_addc_u32 s8, s3, 0
	s_mov_b32 s4, 0
	v_mov_b32_e32 v1, v0
	v_mov_b32_e32 v2, v0
	v_mov_b32_e32 v3, v0
	v_mov_b32_e32 v4, v0
	v_mov_b32_e32 v5, v0
	v_mov_b32_e32 v6, v0
	v_mov_b32_e32 v7, v0
	v_mov_b32_e32 v16, v0
	v_mov_b32_e32 v17, v0
	v_mov_b32_e32 v18, v0
	v_mov_b32_e32 v19, v0
	v_mov_b32_e32 v20, v0
	v_mov_b32_e32 v21, v0
	v_mov_b32_e32 v22, v0
	v_mov_b32_e32 v23, v0
	v_mov_b32_e32 v32, v0
	v_mov_b32_e32 v33, v0
	v_mov_b32_e32 v34, v0
	v_mov_b32_e32 v35, v0
	v_mov_b32_e32 v36, v0
	v_mov_b32_e32 v37, v0
	v_mov_b32_e32 v38, v0
	v_mov_b32_e32 v39, v0
	v_mov_b32_e32 v48, v0
	v_mov_b32_e32 v49, v0
	v_mov_b32_e32 v50, v0
	v_mov_b32_e32 v51, v0
	v_mov_b32_e32 v52, v0
	v_mov_b32_e32 v53, v0
	v_mov_b32_e32 v54, v0
	v_mov_b32_e32 v55, v0
	v_mov_b32_e32 v8, v0
	v_mov_b32_e32 v9, v0
	v_mov_b32_e32 v10, v0
	v_mov_b32_e32 v11, v0
	v_mov_b32_e32 v12, v0
	v_mov_b32_e32 v13, v0
	v_mov_b32_e32 v14, v0
	v_mov_b32_e32 v15, v0
	v_mov_b32_e32 v24, v0
	v_mov_b32_e32 v25, v0
	v_mov_b32_e32 v26, v0
	v_mov_b32_e32 v27, v0
	v_mov_b32_e32 v28, v0
	v_mov_b32_e32 v29, v0
	v_mov_b32_e32 v30, v0
	v_mov_b32_e32 v31, v0
	v_mov_b32_e32 v40, v0
	v_mov_b32_e32 v41, v0
	v_mov_b32_e32 v42, v0
	v_mov_b32_e32 v43, v0
	v_mov_b32_e32 v44, v0
	v_mov_b32_e32 v45, v0
	v_mov_b32_e32 v46, v0
	v_mov_b32_e32 v47, v0
	v_mov_b32_e32 v56, v0
	v_mov_b32_e32 v57, v0
	v_mov_b32_e32 v58, v0
	v_mov_b32_e32 v59, v0
	v_mov_b32_e32 v60, v0
	v_mov_b32_e32 v61, v0
	v_mov_b32_e32 v62, v0
	v_mov_b32_e32 v63, v0
	v_mov_b32_e32 v64, v0
	v_mov_b32_e32 v65, v0
	v_mov_b32_e32 v66, v0
	v_mov_b32_e32 v67, v0
	v_mov_b32_e32 v68, v0
	v_mov_b32_e32 v69, v0
	v_mov_b32_e32 v70, v0
	v_mov_b32_e32 v71, v0
	v_mov_b32_e32 v80, v0
	v_mov_b32_e32 v81, v0
	v_mov_b32_e32 v82, v0
	v_mov_b32_e32 v83, v0
	v_mov_b32_e32 v84, v0
	v_mov_b32_e32 v85, v0
	v_mov_b32_e32 v86, v0
	v_mov_b32_e32 v87, v0
	v_mov_b32_e32 v96, v0
	v_mov_b32_e32 v97, v0
	v_mov_b32_e32 v98, v0
	v_mov_b32_e32 v99, v0
	v_mov_b32_e32 v100, v0
	v_mov_b32_e32 v101, v0
	v_mov_b32_e32 v102, v0
	v_mov_b32_e32 v103, v0
	v_mov_b32_e32 v112, v0
	v_mov_b32_e32 v113, v0
	v_mov_b32_e32 v114, v0
	v_mov_b32_e32 v115, v0
	v_mov_b32_e32 v116, v0
	v_mov_b32_e32 v117, v0
	v_mov_b32_e32 v118, v0
	v_mov_b32_e32 v119, v0
	v_mov_b32_e32 v72, v0
	v_mov_b32_e32 v73, v0
	v_mov_b32_e32 v74, v0
	v_mov_b32_e32 v75, v0
	v_mov_b32_e32 v76, v0
	v_mov_b32_e32 v77, v0
	v_mov_b32_e32 v78, v0
	v_mov_b32_e32 v79, v0
	v_mov_b32_e32 v88, v0
	v_mov_b32_e32 v89, v0
	v_mov_b32_e32 v90, v0
	v_mov_b32_e32 v91, v0
	v_mov_b32_e32 v92, v0
	v_mov_b32_e32 v93, v0
	v_mov_b32_e32 v94, v0
	v_mov_b32_e32 v95, v0
	v_mov_b32_e32 v104, v0
	v_mov_b32_e32 v105, v0
	v_mov_b32_e32 v106, v0
	v_mov_b32_e32 v107, v0
	v_mov_b32_e32 v108, v0
	v_mov_b32_e32 v109, v0
	v_mov_b32_e32 v110, v0
	v_mov_b32_e32 v111, v0
	v_mov_b32_e32 v120, v0
	v_mov_b32_e32 v121, v0
	v_mov_b32_e32 v122, v0
	v_mov_b32_e32 v123, v0
	v_mov_b32_e32 v124, v0
	v_mov_b32_e32 v125, v0
	v_mov_b32_e32 v126, v0
	v_mov_b32_e32 v127, v0
	s_mov_b64 s[58:59], 0x80

; #define LAS __attribute__((address_space(3)))
;     ...
;         const bool has_next = S.next(ui + 1, nxt);
;         const unsigned rsoff = (unsigned)STAGE_BYTES + (unsigned)(ui & 1) * 1024u;
;         if constexpr (Epi::NEEDS_RS) { if (wid < 4) __builtin_amdgcn_global_load_lds((const unsigned*)(E.rsv + cur.pm * 256 + wid * 64 + lane), (LAS unsigned*)(lds + rsoff + wid * 256), 4, 0, 0); }
;         const char* nA = has_next ? (const char*)g.A + (size_t)nxt.pm * tstepA + (size_t)nxt.pn * APN : cA; const char* nB = has_next ? (const char*)g.Bt + (size_t)nxt.pn * tstepB : cB;
;         for (int t = 0; t < nt; t += 2) {
;             const bool last = (t == nt - 2);
;             const char* a1 = cA + (size_t)(t + 1) * kstep;
;             const char* a2 = last ? nA : cA + (size_t)(t + 2) * kstep; const char* b2 = last ? nB : cB + (size_t)(t + 2) * kstep;
;             const char* a3 = a2 + kstep; const char* b3 = b2 + kstep;
;     ...
; #pragma unroll
;         for (int a = 0; a < 2; ++a)
; #pragma unroll
;             for (int b = 0; b < 2; ++b)
; #pragma unroll
;                 for (int m = 0; m < 4; ++m)
; #pragma unroll
;                     for (int n = 0; n < 2; ++n) acc[a][b][m][n] = (f32x4){0.f, 0.f, 0.f, 0.f};
;         cur = nxt; cA = nA; cB = nB; ++ui;
.LBB0_204:
	s_ashr_i32 s17, s16, 31
	s_lshl_b64 s[22:23], s[16:17], 19
	v_readlane_b32 s52, v254, 28
	v_readlane_b32 s53, v254, 29
	s_add_u32 s22, s52, s22
	s_addc_u32 s23, s53, s23
	s_andn2_b64 vcc, exec, s[8:9]
	s_cbranch_vccnz .Lzskip_2
	s_and_b64 s[12:13], s[12:13], exec
	s_cselect_b32 s17, s23, s29
	s_cselect_b32 s52, s22, s28
	s_add_u32 s12, s28, 0x40080
	s_addc_u32 s13, s29, 0
	s_add_u32 s28, s26, 0x100
	v_mov_b32_e32 v0, 0
	s_addc_u32 s29, s27, 0
	s_mov_b32 s26, 0
	v_mov_b32_e32 v1, v0
	v_mov_b32_e32 v2, v0
	v_mov_b32_e32 v3, v0
	v_mov_b32_e32 v8, v0
	v_mov_b32_e32 v9, v0
	v_mov_b32_e32 v10, v0
	v_mov_b32_e32 v11, v0
	v_mov_b32_e32 v16, v0
	v_mov_b32_e32 v17, v0
	v_mov_b32_e32 v18, v0
	v_mov_b32_e32 v19, v0
	v_mov_b32_e32 v24, v0
	v_mov_b32_e32 v25, v0
	v_mov_b32_e32 v26, v0
	v_mov_b32_e32 v27, v0
	v_mov_b32_e32 v32, v0
	v_mov_b32_e32 v33, v0
	v_mov_b32_e32 v34, v0
	v_mov_b32_e32 v35, v0
	v_mov_b32_e32 v40, v0
	v_mov_b32_e32 v41, v0
	v_mov_b32_e32 v42, v0
	v_mov_b32_e32 v43, v0
	v_mov_b32_e32 v48, v0
	v_mov_b32_e32 v49, v0
	v_mov_b32_e32 v50, v0
	v_mov_b32_e32 v51, v0
	v_mov_b32_e32 v56, v0
	v_mov_b32_e32 v57, v0
	v_mov_b32_e32 v58, v0
	v_mov_b32_e32 v59, v0
	v_mov_b32_e32 v4, v0
	v_mov_b32_e32 v5, v0
	v_mov_b32_e32 v6, v0
	v_mov_b32_e32 v7, v0
	v_mov_b32_e32 v12, v0
	v_mov_b32_e32 v13, v0
	v_mov_b32_e32 v14, v0
	v_mov_b32_e32 v15, v0
	v_mov_b32_e32 v20, v0
	v_mov_b32_e32 v21, v0
	v_mov_b32_e32 v22, v0
	v_mov_b32_e32 v23, v0
	v_mov_b32_e32 v28, v0
	v_mov_b32_e32 v29, v0
	v_mov_b32_e32 v30, v0
	v_mov_b32_e32 v31, v0
	v_mov_b32_e32 v36, v0
	v_mov_b32_e32 v37, v0
	v_mov_b32_e32 v38, v0
	v_mov_b32_e32 v39, v0
	v_mov_b32_e32 v44, v0
	v_mov_b32_e32 v45, v0
	v_mov_b32_e32 v46, v0
	v_mov_b32_e32 v47, v0
	v_mov_b32_e32 v52, v0
	v_mov_b32_e32 v53, v0
	v_mov_b32_e32 v54, v0
	v_mov_b32_e32 v55, v0
	v_mov_b32_e32 v60, v0
	v_mov_b32_e32 v61, v0
	v_mov_b32_e32 v62, v0
	v_mov_b32_e32 v63, v0
	v_mov_b32_e32 v64, v0
	v_mov_b32_e32 v65, v0
	v_mov_b32_e32 v66, v0
	v_mov_b32_e32 v67, v0
	v_mov_b32_e32 v72, v0
	v_mov_b32_e32 v73, v0
	v_mov_b32_e32 v74, v0
	v_mov_b32_e32 v75, v0
	v_mov_b32_e32 v80, v0
	v_mov_b32_e32 v81, v0
	v_mov_b32_e32 v82, v0
	v_mov_b32_e32 v83, v0
	v_mov_b32_e32 v88, v0
	v_mov_b32_e32 v89, v0
	v_mov_b32_e32 v90, v0
	v_mov_b32_e32 v91, v0
	v_mov_b32_e32 v96, v0
	v_mov_b32_e32 v97, v0
	v_mov_b32_e32 v98, v0
	v_mov_b32_e32 v99, v0
	v_mov_b32_e32 v104, v0
	v_mov_b32_e32 v105, v0
	v_mov_b32_e32 v106, v0
	v_mov_b32_e32 v107, v0
	v_mov_b32_e32 v112, v0
	v_mov_b32_e32 v113, v0
	v_mov_b32_e32 v114, v0
	v_mov_b32_e32 v115, v0
	v_mov_b32_e32 v120, v0
	v_mov_b32_e32 v121, v0
	v_mov_b32_e32 v122, v0
	v_mov_b32_e32 v123, v0
	v_mov_b32_e32 v68, v0
	v_mov_b32_e32 v69, v0
	v_mov_b32_e32 v70, v0
	v_mov_b32_e32 v71, v0
	v_mov_b32_e32 v76, v0
	v_mov_b32_e32 v77, v0
	v_mov_b32_e32 v78, v0
	v_mov_b32_e32 v79, v0
	v_mov_b32_e32 v84, v0
	v_mov_b32_e32 v85, v0
	v_mov_b32_e32 v86, v0
	v_mov_b32_e32 v87, v0
	v_mov_b32_e32 v92, v0
	v_mov_b32_e32 v93, v0
	v_mov_b32_e32 v94, v0
	v_mov_b32_e32 v95, v0
	v_mov_b32_e32 v100, v0
	v_mov_b32_e32 v101, v0
	v_mov_b32_e32 v102, v0
	v_mov_b32_e32 v103, v0
	v_mov_b32_e32 v108, v0
	v_mov_b32_e32 v109, v0
	v_mov_b32_e32 v110, v0
	v_mov_b32_e32 v111, v0
	v_mov_b32_e32 v116, v0
	v_mov_b32_e32 v117, v0
	v_mov_b32_e32 v118, v0
	v_mov_b32_e32 v119, v0
	v_mov_b32_e32 v124, v0
	v_mov_b32_e32 v125, v0
	v_mov_b32_e32 v126, v0
	v_mov_b32_e32 v127, v0
	s_mov_b64 s[58:59], 0x80

;     ...
; #pragma unroll
;         for (int a = 0; a < 2; ++a)
; #pragma unroll
;             for (int b = 0; b < 2; ++b)
; #pragma unroll
;                 for (int m = 0; m < 4; ++m)
; #pragma unroll
;                     for (int n = 0; n < 2; ++n) acc[a][b][m][n] = (f32x4){0.f, 0.f, 0.f, 0.f};
.Lzskip_2:
	v_mov_b32_e32 v127, 0
	v_mov_b32_e32 v126, v127
	v_mov_b32_e32 v125, v127
	v_mov_b32_e32 v124, v127
	v_mov_b32_e32 v119, v127
	v_mov_b32_e32 v118, v127
	v_mov_b32_e32 v117, v127
	v_mov_b32_e32 v116, v127
	v_mov_b32_e32 v111, v127
	v_mov_b32_e32 v110, v127
	v_mov_b32_e32 v109, v127
	v_mov_b32_e32 v108, v127
	v_mov_b32_e32 v103, v127
	v_mov_b32_e32 v102, v127
	v_mov_b32_e32 v101, v127
	v_mov_b32_e32 v100, v127
	v_mov_b32_e32 v95, v127
	v_mov_b32_e32 v94, v127
	v_mov_b32_e32 v93, v127
	v_mov_b32_e32 v92, v127
	v_mov_b32_e32 v87, v127
	v_mov_b32_e32 v86, v127
	v_mov_b32_e32 v85, v127
	v_mov_b32_e32 v84, v127
	v_mov_b32_e32 v79, v127
	v_mov_b32_e32 v78, v127
	v_mov_b32_e32 v77, v127
	v_mov_b32_e32 v76, v127
	v_mov_b32_e32 v71, v127
	v_mov_b32_e32 v70, v127
	v_mov_b32_e32 v69, v127
	v_mov_b32_e32 v68, v127
	v_mov_b32_e32 v123, v127
	v_mov_b32_e32 v122, v127
	v_mov_b32_e32 v121, v127
	v_mov_b32_e32 v120, v127
	v_mov_b32_e32 v115, v127
	v_mov_b32_e32 v114, v127
	v_mov_b32_e32 v113, v127
	v_mov_b32_e32 v112, v127
	v_mov_b32_e32 v107, v127
	v_mov_b32_e32 v106, v127
	v_mov_b32_e32 v105, v127
	v_mov_b32_e32 v104, v127
	v_mov_b32_e32 v99, v127
	v_mov_b32_e32 v98, v127
	v_mov_b32_e32 v97, v127
	v_mov_b32_e32 v96, v127
	v_mov_b32_e32 v91, v127
	v_mov_b32_e32 v90, v127
	v_mov_b32_e32 v89, v127
	v_mov_b32_e32 v88, v127
	v_mov_b32_e32 v83, v127
	v_mov_b32_e32 v82, v127
	v_mov_b32_e32 v81, v127
	v_mov_b32_e32 v80, v127
	v_mov_b32_e32 v75, v127
	v_mov_b32_e32 v74, v127
	v_mov_b32_e32 v73, v127
	v_mov_b32_e32 v72, v127
	v_mov_b32_e32 v67, v127
	v_mov_b32_e32 v66, v127
	v_mov_b32_e32 v65, v127
	v_mov_b32_e32 v64, v127
	v_mov_b32_e32 v63, v127
	v_mov_b32_e32 v62, v127
	v_mov_b32_e32 v61, v127
	v_mov_b32_e32 v60, v127
	v_mov_b32_e32 v55, v127
	v_mov_b32_e32 v54, v127
	v_mov_b32_e32 v53, v127
	v_mov_b32_e32 v52, v127
	v_mov_b32_e32 v47, v127
	v_mov_b32_e32 v46, v127
	v_mov_b32_e32 v45, v127
	v_mov_b32_e32 v44, v127
	v_mov_b32_e32 v39, v127
	v_mov_b32_e32 v38, v127
	v_mov_b32_e32 v37, v127
	v_mov_b32_e32 v36, v127
	v_mov_b32_e32 v31, v127
	v_mov_b32_e32 v30, v127
	v_mov_b32_e32 v29, v127
	v_mov_b32_e32 v28, v127
	v_mov_b32_e32 v23, v127
	v_mov_b32_e32 v22, v127
	v_mov_b32_e32 v21, v127
	v_mov_b32_e32 v20, v127
	v_mov_b32_e32 v15, v127
	v_mov_b32_e32 v14, v127
	v_mov_b32_e32 v13, v127
	v_mov_b32_e32 v12, v127
	v_mov_b32_e32 v7, v127
	v_mov_b32_e32 v6, v127
	v_mov_b32_e32 v5, v127
	v_mov_b32_e32 v4, v127
	v_mov_b32_e32 v59, v127
	v_mov_b32_e32 v58, v127
	v_mov_b32_e32 v57, v127
	v_mov_b32_e32 v56, v127
	v_mov_b32_e32 v51, v127
	v_mov_b32_e32 v50, v127
	v_mov_b32_e32 v49, v127
	v_mov_b32_e32 v48, v127
	v_mov_b32_e32 v43, v127
	v_mov_b32_e32 v42, v127
	v_mov_b32_e32 v41, v127
	v_mov_b32_e32 v40, v127
	v_mov_b32_e32 v35, v127
	v_mov_b32_e32 v34, v127
	v_mov_b32_e32 v33, v127
	v_mov_b32_e32 v32, v127
	v_mov_b32_e32 v27, v127
	v_mov_b32_e32 v26, v127
	v_mov_b32_e32 v25, v127
	v_mov_b32_e32 v24, v127
	v_mov_b32_e32 v19, v127
	v_mov_b32_e32 v18, v127
	v_mov_b32_e32 v17, v127
	v_mov_b32_e32 v16, v127
	v_mov_b32_e32 v11, v127
	v_mov_b32_e32 v10, v127
	v_mov_b32_e32 v9, v127
	v_mov_b32_e32 v8, v127
	v_mov_b32_e32 v3, v127
	v_mov_b32_e32 v2, v127
	v_mov_b32_e32 v1, v127
	v_mov_b32_e32 v0, v127
	s_branch .LBB0_207

; #define LAS __attribute__((address_space(3)))
;     ...
;         const bool has_next = S.next(ui + 1, nxt);
;         const unsigned rsoff = (unsigned)STAGE_BYTES + (unsigned)(ui & 1) * 1024u;
;         if constexpr (Epi::NEEDS_RS) { if (wid < 4) __builtin_amdgcn_global_load_lds((const unsigned*)(E.rsv + cur.pm * 256 + wid * 64 + lane), (LAS unsigned*)(lds + rsoff + wid * 256), 4, 0, 0); }
;         const char* nA = has_next ? (const char*)g.A + (size_t)nxt.pm * tstepA + (size_t)nxt.pn * APN : cA; const char* nB = has_next ? (const char*)g.Bt + (size_t)nxt.pn * tstepB : cB;
;         for (int t = 0; t < nt; t += 2) {
;             const bool last = (t == nt - 2);
;             const char* a1 = cA + (size_t)(t + 1) * kstep;
;             const char* a2 = last ? nA : cA + (size_t)(t + 2) * kstep; const char* b2 = last ? nB : cB + (size_t)(t + 2) * kstep;
;             const char* a3 = a2 + kstep; const char* b3 = b2 + kstep;
;     ...
; #pragma unroll
;         for (int a = 0; a < 2; ++a)
; #pragma unroll
;             for (int b = 0; b < 2; ++b)
; #pragma unroll
;                 for (int m = 0; m < 4; ++m)
; #pragma unroll
;                     for (int n = 0; n < 2; ++n) acc[a][b][m][n] = (f32x4){0.f, 0.f, 0.f, 0.f};
;         cur = nxt; cA = nA; cB = nB; ++ui;
.LBB0_283:
	s_ashr_i32 s19, s18, 31
	s_lshl_b64 s[24:25], s[18:19], 18
	s_add_u32 s19, s38, s24
	s_addc_u32 s53, s39, s25
	s_lshl_b64 s[24:25], s[16:17], 8
	s_add_u32 s24, s19, s24
	s_addc_u32 s25, s53, s25
	s_andn2_b64 vcc, exec, s[4:5]
	s_cbranch_vccnz .Lzskip_4
	s_and_b64 s[12:13], s[12:13], exec
	s_cselect_b32 s17, s25, s31
	s_cselect_b32 s19, s24, s30
	s_add_u32 s12, s30, 0x20080
	s_addc_u32 s13, s31, 0
	s_add_u32 s30, s28, 0x100
	v_mov_b32_e32 v0, 0
	s_addc_u32 s31, s29, 0
	s_mov_b32 s28, 0
	v_mov_b32_e32 v1, v0
	v_mov_b32_e32 v2, v0
	v_mov_b32_e32 v3, v0
	v_mov_b32_e32 v4, v0
	v_mov_b32_e32 v5, v0
	v_mov_b32_e32 v6, v0
	v_mov_b32_e32 v7, v0
	v_mov_b32_e32 v8, v0
	v_mov_b32_e32 v9, v0
	v_mov_b32_e32 v10, v0
	v_mov_b32_e32 v11, v0
	v_mov_b32_e32 v12, v0
	v_mov_b32_e32 v13, v0
	v_mov_b32_e32 v14, v0
	v_mov_b32_e32 v15, v0
	v_mov_b32_e32 v16, v0
	v_mov_b32_e32 v17, v0
	v_mov_b32_e32 v18, v0
	v_mov_b32_e32 v19, v0
	v_mov_b32_e32 v20, v0
	v_mov_b32_e32 v21, v0
	v_mov_b32_e32 v22, v0
	v_mov_b32_e32 v23, v0
	v_mov_b32_e32 v24, v0
	v_mov_b32_e32 v25, v0
	v_mov_b32_e32 v26, v0
	v_mov_b32_e32 v27, v0
	v_mov_b32_e32 v28, v0
	v_mov_b32_e32 v29, v0
	v_mov_b32_e32 v30, v0
	v_mov_b32_e32 v31, v0
	v_mov_b32_e32 v64, v0
	v_mov_b32_e32 v65, v0
	v_mov_b32_e32 v66, v0
	v_mov_b32_e32 v67, v0
	v_mov_b32_e32 v68, v0
	v_mov_b32_e32 v69, v0
	v_mov_b32_e32 v70, v0
	v_mov_b32_e32 v71, v0
	v_mov_b32_e32 v72, v0
	v_mov_b32_e32 v73, v0
	v_mov_b32_e32 v74, v0
	v_mov_b32_e32 v75, v0
	v_mov_b32_e32 v76, v0
	v_mov_b32_e32 v77, v0
	v_mov_b32_e32 v78, v0
	v_mov_b32_e32 v79, v0
	v_mov_b32_e32 v80, v0
	v_mov_b32_e32 v81, v0
	v_mov_b32_e32 v82, v0
	v_mov_b32_e32 v83, v0
	v_mov_b32_e32 v84, v0
	v_mov_b32_e32 v85, v0
	v_mov_b32_e32 v86, v0
	v_mov_b32_e32 v87, v0
	v_mov_b32_e32 v88, v0
	v_mov_b32_e32 v89, v0
	v_mov_b32_e32 v90, v0
	v_mov_b32_e32 v91, v0
	v_mov_b32_e32 v92, v0
	v_mov_b32_e32 v93, v0
	v_mov_b32_e32 v94, v0
	v_mov_b32_e32 v95, v0
	v_mov_b32_e32 v32, v0
	v_mov_b32_e32 v33, v0
	v_mov_b32_e32 v34, v0
	v_mov_b32_e32 v35, v0
	v_mov_b32_e32 v36, v0
	v_mov_b32_e32 v37, v0
	v_mov_b32_e32 v38, v0
	v_mov_b32_e32 v39, v0
	v_mov_b32_e32 v40, v0
	v_mov_b32_e32 v41, v0
	v_mov_b32_e32 v42, v0
	v_mov_b32_e32 v43, v0
	v_mov_b32_e32 v44, v0
	v_mov_b32_e32 v45, v0
	v_mov_b32_e32 v46, v0
	v_mov_b32_e32 v47, v0
	v_mov_b32_e32 v48, v0
	v_mov_b32_e32 v49, v0
	v_mov_b32_e32 v50, v0
	v_mov_b32_e32 v51, v0
	v_mov_b32_e32 v52, v0
	v_mov_b32_e32 v53, v0
	v_mov_b32_e32 v54, v0
	v_mov_b32_e32 v55, v0
	v_mov_b32_e32 v56, v0
	v_mov_b32_e32 v57, v0
	v_mov_b32_e32 v58, v0
	v_mov_b32_e32 v59, v0
	v_mov_b32_e32 v60, v0
	v_mov_b32_e32 v61, v0
	v_mov_b32_e32 v62, v0
	v_mov_b32_e32 v63, v0
	v_mov_b32_e32 v96, v0
	v_mov_b32_e32 v97, v0
	v_mov_b32_e32 v98, v0
	v_mov_b32_e32 v99, v0
	v_mov_b32_e32 v100, v0
	v_mov_b32_e32 v101, v0
	v_mov_b32_e32 v102, v0
	v_mov_b32_e32 v103, v0
	v_mov_b32_e32 v104, v0
	v_mov_b32_e32 v105, v0
	v_mov_b32_e32 v106, v0
	v_mov_b32_e32 v107, v0
	v_mov_b32_e32 v108, v0
	v_mov_b32_e32 v109, v0
	v_mov_b32_e32 v110, v0
	v_mov_b32_e32 v111, v0
	v_mov_b32_e32 v120, v0
	v_mov_b32_e32 v121, v0
	v_mov_b32_e32 v122, v0
	v_mov_b32_e32 v123, v0
	v_mov_b32_e32 v124, v0
	v_mov_b32_e32 v125, v0
	v_mov_b32_e32 v126, v0
	v_mov_b32_e32 v127, v0
	v_mov_b32_e32 v132, v0
	v_mov_b32_e32 v133, v0
	v_mov_b32_e32 v134, v0
	v_mov_b32_e32 v135, v0
	v_mov_b32_e32 v128, v0
	v_mov_b32_e32 v129, v0
	v_mov_b32_e32 v130, v0
	v_mov_b32_e32 v131, v0
	s_mov_b64 s[58:59], 0x80

;     ...
; #pragma unroll
;         for (int a = 0; a < 2; ++a)
; #pragma unroll
;             for (int b = 0; b < 2; ++b)
; #pragma unroll
;                 for (int m = 0; m < 4; ++m)
; #pragma unroll
;                     for (int n = 0; n < 2; ++n) acc[a][b][m][n] = (f32x4){0.f, 0.f, 0.f, 0.f};
.Lzskip_4:
	v_mov_b32_e32 v131, 0
	v_mov_b32_e32 v130, v131
	v_mov_b32_e32 v129, v131
	v_mov_b32_e32 v128, v131
	v_mov_b32_e32 v135, v131
	v_mov_b32_e32 v134, v131
	v_mov_b32_e32 v133, v131
	v_mov_b32_e32 v132, v131
	v_mov_b32_e32 v127, v131
	v_mov_b32_e32 v126, v131
	v_mov_b32_e32 v125, v131
	v_mov_b32_e32 v124, v131
	v_mov_b32_e32 v123, v131
	v_mov_b32_e32 v122, v131
	v_mov_b32_e32 v121, v131
	v_mov_b32_e32 v120, v131
	v_mov_b32_e32 v111, v131
	v_mov_b32_e32 v110, v131
	v_mov_b32_e32 v109, v131
	v_mov_b32_e32 v108, v131
	v_mov_b32_e32 v107, v131
	v_mov_b32_e32 v106, v131
	v_mov_b32_e32 v105, v131
	v_mov_b32_e32 v104, v131
	v_mov_b32_e32 v103, v131
	v_mov_b32_e32 v102, v131
	v_mov_b32_e32 v101, v131
	v_mov_b32_e32 v100, v131
	v_mov_b32_e32 v99, v131
	v_mov_b32_e32 v98, v131
	v_mov_b32_e32 v97, v131
	v_mov_b32_e32 v96, v131
	v_mov_b32_e32 v63, v131
	v_mov_b32_e32 v62, v131
	v_mov_b32_e32 v61, v131
	v_mov_b32_e32 v60, v131
	v_mov_b32_e32 v59, v131
	v_mov_b32_e32 v58, v131
	v_mov_b32_e32 v57, v131
	v_mov_b32_e32 v56, v131
	v_mov_b32_e32 v55, v131
	v_mov_b32_e32 v54, v131
	v_mov_b32_e32 v53, v131
	v_mov_b32_e32 v52, v131
	v_mov_b32_e32 v51, v131
	v_mov_b32_e32 v50, v131
	v_mov_b32_e32 v49, v131
	v_mov_b32_e32 v48, v131
	v_mov_b32_e32 v47, v131
	v_mov_b32_e32 v46, v131
	v_mov_b32_e32 v45, v131
	v_mov_b32_e32 v44, v131
	v_mov_b32_e32 v43, v131
	v_mov_b32_e32 v42, v131
	v_mov_b32_e32 v41, v131
	v_mov_b32_e32 v40, v131
	v_mov_b32_e32 v39, v131
	v_mov_b32_e32 v38, v131
	v_mov_b32_e32 v37, v131
	v_mov_b32_e32 v36, v131
	v_mov_b32_e32 v35, v131
	v_mov_b32_e32 v34, v131
	v_mov_b32_e32 v33, v131
	v_mov_b32_e32 v32, v131
	v_mov_b32_e32 v95, v131
	v_mov_b32_e32 v94, v131
	v_mov_b32_e32 v93, v131
	v_mov_b32_e32 v92, v131
	v_mov_b32_e32 v91, v131
	v_mov_b32_e32 v90, v131
	v_mov_b32_e32 v89, v131
	v_mov_b32_e32 v88, v131
	v_mov_b32_e32 v87, v131
	v_mov_b32_e32 v86, v131
	v_mov_b32_e32 v85, v131
	v_mov_b32_e32 v84, v131
	v_mov_b32_e32 v83, v131
	v_mov_b32_e32 v82, v131
	v_mov_b32_e32 v81, v131
	v_mov_b32_e32 v80, v131
	v_mov_b32_e32 v79, v131
	v_mov_b32_e32 v78, v131
	v_mov_b32_e32 v77, v131
	v_mov_b32_e32 v76, v131
	v_mov_b32_e32 v75, v131
	v_mov_b32_e32 v74, v131
	v_mov_b32_e32 v73, v131
	v_mov_b32_e32 v72, v131
	v_mov_b32_e32 v71, v131
	v_mov_b32_e32 v70, v131
	v_mov_b32_e32 v69, v131
	v_mov_b32_e32 v68, v131
	v_mov_b32_e32 v67, v131
	v_mov_b32_e32 v66, v131
	v_mov_b32_e32 v65, v131
	v_mov_b32_e32 v64, v131
	v_mov_b32_e32 v31, v131
	v_mov_b32_e32 v30, v131
	v_mov_b32_e32 v29, v131
	v_mov_b32_e32 v28, v131
	v_mov_b32_e32 v27, v131
	v_mov_b32_e32 v26, v131
	v_mov_b32_e32 v25, v131
	v_mov_b32_e32 v24, v131
	v_mov_b32_e32 v23, v131
	v_mov_b32_e32 v22, v131
	v_mov_b32_e32 v21, v131
	v_mov_b32_e32 v20, v131
	v_mov_b32_e32 v19, v131
	v_mov_b32_e32 v18, v131
	v_mov_b32_e32 v17, v131
	v_mov_b32_e32 v16, v131
	v_mov_b32_e32 v15, v131
	v_mov_b32_e32 v14, v131
	v_mov_b32_e32 v13, v131
	v_mov_b32_e32 v12, v131
	v_mov_b32_e32 v11, v131
	v_mov_b32_e32 v10, v131
	v_mov_b32_e32 v9, v131
	v_mov_b32_e32 v8, v131
	v_mov_b32_e32 v7, v131
	v_mov_b32_e32 v6, v131
	v_mov_b32_e32 v5, v131
	v_mov_b32_e32 v4, v131
	v_mov_b32_e32 v3, v131
	v_mov_b32_e32 v2, v131
	v_mov_b32_e32 v1, v131
	v_mov_b32_e32 v0, v131
	s_branch .LBB0_286

; #define LAS __attribute__((address_space(3)))
;     ...
;         const bool has_next = S.next(ui + 1, nxt);
;         const unsigned rsoff = (unsigned)STAGE_BYTES + (unsigned)(ui & 1) * 1024u;
;         if constexpr (Epi::NEEDS_RS) { if (wid < 4) __builtin_amdgcn_global_load_lds((const unsigned*)(E.rsv + cur.pm * 256 + wid * 64 + lane), (LAS unsigned*)(lds + rsoff + wid * 256), 4, 0, 0); }
;         const char* nA = has_next ? (const char*)g.A + (size_t)nxt.pm * tstepA + (size_t)nxt.pn * APN : cA; const char* nB = has_next ? (const char*)g.Bt + (size_t)nxt.pn * tstepB : cB;
;         for (int t = 0; t < nt; t += 2) {
;             const bool last = (t == nt - 2);
;             const char* a1 = cA + (size_t)(t + 1) * kstep;
;             const char* a2 = last ? nA : cA + (size_t)(t + 2) * kstep; const char* b2 = last ? nB : cB + (size_t)(t + 2) * kstep;
;             const char* a3 = a2 + kstep; const char* b3 = b2 + kstep;
;     ...
; #pragma unroll
;         for (int a = 0; a < 2; ++a)
; #pragma unroll
;             for (int b = 0; b < 2; ++b)
; #pragma unroll
;                 for (int m = 0; m < 4; ++m)
; #pragma unroll
;                     for (int n = 0; n < 2; ++n) acc[a][b][m][n] = (f32x4){0.f, 0.f, 0.f, 0.f};
;         cur = nxt; cA = nA; cB = nB; ++ui;
.LBB0_312:
	s_andn2_b64 vcc, exec, s[22:23]
	s_cbranch_vccnz .Lzskip_5
	s_add_u32 s48, s2, 0x100
	v_mov_b32_e32 v0, 0
	s_addc_u32 s49, s3, 0
	s_mov_b32 s4, 0
	v_mov_b32_e32 v1, v0
	v_mov_b32_e32 v2, v0
	v_mov_b32_e32 v3, v0
	v_mov_b32_e32 v4, v0
	v_mov_b32_e32 v5, v0
	v_mov_b32_e32 v6, v0
	v_mov_b32_e32 v7, v0
	v_mov_b32_e32 v16, v0
	v_mov_b32_e32 v17, v0
	v_mov_b32_e32 v18, v0
	v_mov_b32_e32 v19, v0
	v_mov_b32_e32 v20, v0
	v_mov_b32_e32 v21, v0
	v_mov_b32_e32 v22, v0
	v_mov_b32_e32 v23, v0
	v_mov_b32_e32 v32, v0
	v_mov_b32_e32 v33, v0
	v_mov_b32_e32 v34, v0
	v_mov_b32_e32 v35, v0
	v_mov_b32_e32 v36, v0
	v_mov_b32_e32 v37, v0
	v_mov_b32_e32 v38, v0
	v_mov_b32_e32 v39, v0
	v_mov_b32_e32 v48, v0
	v_mov_b32_e32 v49, v0
	v_mov_b32_e32 v50, v0
	v_mov_b32_e32 v51, v0
	v_mov_b32_e32 v52, v0
	v_mov_b32_e32 v53, v0
	v_mov_b32_e32 v54, v0
	v_mov_b32_e32 v55, v0
	v_mov_b32_e32 v8, v0
	v_mov_b32_e32 v9, v0
	v_mov_b32_e32 v10, v0
	v_mov_b32_e32 v11, v0
	v_mov_b32_e32 v12, v0
	v_mov_b32_e32 v13, v0
	v_mov_b32_e32 v14, v0
	v_mov_b32_e32 v15, v0
	v_mov_b32_e32 v24, v0
	v_mov_b32_e32 v25, v0
	v_mov_b32_e32 v26, v0
	v_mov_b32_e32 v27, v0
	v_mov_b32_e32 v28, v0
	v_mov_b32_e32 v29, v0
	v_mov_b32_e32 v30, v0
	v_mov_b32_e32 v31, v0
	v_mov_b32_e32 v40, v0
	v_mov_b32_e32 v41, v0
	v_mov_b32_e32 v42, v0
	v_mov_b32_e32 v43, v0
	v_mov_b32_e32 v44, v0
	v_mov_b32_e32 v45, v0
	v_mov_b32_e32 v46, v0
	v_mov_b32_e32 v47, v0
	v_mov_b32_e32 v56, v0
	v_mov_b32_e32 v57, v0
	v_mov_b32_e32 v58, v0
	v_mov_b32_e32 v59, v0
	v_mov_b32_e32 v60, v0
	v_mov_b32_e32 v61, v0
	v_mov_b32_e32 v62, v0
	v_mov_b32_e32 v63, v0
	v_mov_b32_e32 v64, v0
	v_mov_b32_e32 v65, v0
	v_mov_b32_e32 v66, v0
	v_mov_b32_e32 v67, v0
	v_mov_b32_e32 v68, v0
	v_mov_b32_e32 v69, v0
	v_mov_b32_e32 v70, v0
	v_mov_b32_e32 v71, v0
	v_mov_b32_e32 v80, v0
	v_mov_b32_e32 v81, v0
	v_mov_b32_e32 v82, v0
	v_mov_b32_e32 v83, v0
	v_mov_b32_e32 v84, v0
	v_mov_b32_e32 v85, v0
	v_mov_b32_e32 v86, v0
	v_mov_b32_e32 v87, v0
	v_mov_b32_e32 v96, v0
	v_mov_b32_e32 v97, v0
	v_mov_b32_e32 v98, v0
	v_mov_b32_e32 v99, v0
	v_mov_b32_e32 v100, v0
	v_mov_b32_e32 v101, v0
	v_mov_b32_e32 v102, v0
	v_mov_b32_e32 v103, v0
	v_mov_b32_e32 v112, v0
	v_mov_b32_e32 v113, v0
	v_mov_b32_e32 v114, v0
	v_mov_b32_e32 v115, v0
	v_mov_b32_e32 v116, v0
	v_mov_b32_e32 v117, v0
	v_mov_b32_e32 v118, v0
	v_mov_b32_e32 v119, v0
	v_mov_b32_e32 v72, v0
	v_mov_b32_e32 v73, v0
	v_mov_b32_e32 v74, v0
	v_mov_b32_e32 v75, v0
	v_mov_b32_e32 v76, v0
	v_mov_b32_e32 v77, v0
	v_mov_b32_e32 v78, v0
	v_mov_b32_e32 v79, v0
	v_mov_b32_e32 v88, v0
	v_mov_b32_e32 v89, v0
	v_mov_b32_e32 v90, v0
	v_mov_b32_e32 v91, v0
	v_mov_b32_e32 v92, v0
	v_mov_b32_e32 v93, v0
	v_mov_b32_e32 v94, v0
	v_mov_b32_e32 v95, v0
	v_mov_b32_e32 v104, v0
	v_mov_b32_e32 v105, v0
	v_mov_b32_e32 v106, v0
	v_mov_b32_e32 v107, v0
	v_mov_b32_e32 v108, v0
	v_mov_b32_e32 v109, v0
	v_mov_b32_e32 v110, v0
	v_mov_b32_e32 v111, v0
	v_mov_b32_e32 v120, v0
	v_mov_b32_e32 v121, v0
	v_mov_b32_e32 v122, v0
	v_mov_b32_e32 v123, v0
	v_mov_b32_e32 v124, v0
	v_mov_b32_e32 v125, v0
	v_mov_b32_e32 v126, v0
	v_mov_b32_e32 v127, v0
	s_mov_b64 s[56:57], 0x80

; #define LAS __attribute__((address_space(3)))
;     ...
;         const bool has_next = S.next(ui + 1, nxt);
;         const unsigned rsoff = (unsigned)STAGE_BYTES + (unsigned)(ui & 1) * 1024u;
;         if constexpr (Epi::NEEDS_RS) { if (wid < 4) __builtin_amdgcn_global_load_lds((const unsigned*)(E.rsv + cur.pm * 256 + wid * 64 + lane), (LAS unsigned*)(lds + rsoff + wid * 256), 4, 0, 0); }
;         const char* nA = has_next ? (const char*)g.A + (size_t)nxt.pm * tstepA + (size_t)nxt.pn * APN : cA; const char* nB = has_next ? (const char*)g.Bt + (size_t)nxt.pn * tstepB : cB;
;         for (int t = 0; t < nt; t += 2) {
;             const bool last = (t == nt - 2);
;             const char* a1 = cA + (size_t)(t + 1) * kstep;
;             const char* a2 = last ? nA : cA + (size_t)(t + 2) * kstep; const char* b2 = last ? nB : cB + (size_t)(t + 2) * kstep;
;             const char* a3 = a2 + kstep; const char* b3 = b2 + kstep;
;     ...
; #pragma unroll
;         for (int a = 0; a < 2; ++a)
; #pragma unroll
;             for (int b = 0; b < 2; ++b)
; #pragma unroll
;                 for (int m = 0; m < 4; ++m)
; #pragma unroll
;                     for (int n = 0; n < 2; ++n) acc[a][b][m][n] = (f32x4){0.f, 0.f, 0.f, 0.f};
;         cur = nxt; cA = nA; cB = nB; ++ui;
.LBB0_343:
	s_ashr_i32 s17, s16, 31
	s_lshl_b64 s[22:23], s[16:17], 19
	v_readlane_b32 s52, v254, 28
	v_readlane_b32 s53, v254, 29
	s_add_u32 s22, s52, s22
	s_addc_u32 s23, s53, s23
	s_andn2_b64 vcc, exec, s[8:9]
	s_cbranch_vccnz .Lzskip_6
	s_and_b64 s[12:13], s[12:13], exec
	s_cselect_b32 s17, s23, s29
	s_cselect_b32 s52, s22, s28
	s_add_u32 s12, s28, 0x40080
	s_addc_u32 s13, s29, 0
	s_add_u32 s28, s26, 0x100
	v_mov_b32_e32 v0, 0
	s_addc_u32 s29, s27, 0
	s_mov_b32 s26, 0
	v_mov_b32_e32 v1, v0
	v_mov_b32_e32 v2, v0
	v_mov_b32_e32 v3, v0
	v_mov_b32_e32 v4, v0
	v_mov_b32_e32 v5, v0
	v_mov_b32_e32 v6, v0
	v_mov_b32_e32 v7, v0
	v_mov_b32_e32 v16, v0
	v_mov_b32_e32 v17, v0
	v_mov_b32_e32 v18, v0
	v_mov_b32_e32 v19, v0
	v_mov_b32_e32 v20, v0
	v_mov_b32_e32 v21, v0
	v_mov_b32_e32 v22, v0
	v_mov_b32_e32 v23, v0
	v_mov_b32_e32 v32, v0
	v_mov_b32_e32 v33, v0
	v_mov_b32_e32 v34, v0
	v_mov_b32_e32 v35, v0
	v_mov_b32_e32 v36, v0
	v_mov_b32_e32 v37, v0
	v_mov_b32_e32 v38, v0
	v_mov_b32_e32 v39, v0
	v_mov_b32_e32 v48, v0
	v_mov_b32_e32 v49, v0
	v_mov_b32_e32 v50, v0
	v_mov_b32_e32 v51, v0
	v_mov_b32_e32 v52, v0
	v_mov_b32_e32 v53, v0
	v_mov_b32_e32 v54, v0
	v_mov_b32_e32 v55, v0
	v_mov_b32_e32 v8, v0
	v_mov_b32_e32 v9, v0
	v_mov_b32_e32 v10, v0
	v_mov_b32_e32 v11, v0
	v_mov_b32_e32 v12, v0
	v_mov_b32_e32 v13, v0
	v_mov_b32_e32 v14, v0
	v_mov_b32_e32 v15, v0
	v_mov_b32_e32 v24, v0
	v_mov_b32_e32 v25, v0
	v_mov_b32_e32 v26, v0
	v_mov_b32_e32 v27, v0
	v_mov_b32_e32 v28, v0
	v_mov_b32_e32 v29, v0
	v_mov_b32_e32 v30, v0
	v_mov_b32_e32 v31, v0
	v_mov_b32_e32 v40, v0
	v_mov_b32_e32 v41, v0
	v_mov_b32_e32 v42, v0
	v_mov_b32_e32 v43, v0
	v_mov_b32_e32 v44, v0
	v_mov_b32_e32 v45, v0
	v_mov_b32_e32 v46, v0
	v_mov_b32_e32 v47, v0
	v_mov_b32_e32 v56, v0
	v_mov_b32_e32 v57, v0
	v_mov_b32_e32 v58, v0
	v_mov_b32_e32 v59, v0
	v_mov_b32_e32 v60, v0
	v_mov_b32_e32 v61, v0
	v_mov_b32_e32 v62, v0
	v_mov_b32_e32 v63, v0
	v_mov_b32_e32 v64, v0
	v_mov_b32_e32 v65, v0
	v_mov_b32_e32 v66, v0
	v_mov_b32_e32 v67, v0
	v_mov_b32_e32 v68, v0
	v_mov_b32_e32 v69, v0
	v_mov_b32_e32 v70, v0
	v_mov_b32_e32 v71, v0
	v_mov_b32_e32 v80, v0
	v_mov_b32_e32 v81, v0
	v_mov_b32_e32 v82, v0
	v_mov_b32_e32 v83, v0
	v_mov_b32_e32 v84, v0
	v_mov_b32_e32 v85, v0
	v_mov_b32_e32 v86, v0
	v_mov_b32_e32 v87, v0
	v_mov_b32_e32 v96, v0
	v_mov_b32_e32 v97, v0
	v_mov_b32_e32 v98, v0
	v_mov_b32_e32 v99, v0
	v_mov_b32_e32 v100, v0
	v_mov_b32_e32 v101, v0
	v_mov_b32_e32 v102, v0
	v_mov_b32_e32 v103, v0
	v_mov_b32_e32 v112, v0
	v_mov_b32_e32 v113, v0
	v_mov_b32_e32 v114, v0
	v_mov_b32_e32 v115, v0
	v_mov_b32_e32 v116, v0
	v_mov_b32_e32 v117, v0
	v_mov_b32_e32 v118, v0
	v_mov_b32_e32 v119, v0
	v_mov_b32_e32 v72, v0
	v_mov_b32_e32 v73, v0
	v_mov_b32_e32 v74, v0
	v_mov_b32_e32 v75, v0
	v_mov_b32_e32 v76, v0
	v_mov_b32_e32 v77, v0
	v_mov_b32_e32 v78, v0
	v_mov_b32_e32 v79, v0
	v_mov_b32_e32 v88, v0
	v_mov_b32_e32 v89, v0
	v_mov_b32_e32 v90, v0
	v_mov_b32_e32 v91, v0
	v_mov_b32_e32 v92, v0
	v_mov_b32_e32 v93, v0
	v_mov_b32_e32 v94, v0
	v_mov_b32_e32 v95, v0
	v_mov_b32_e32 v104, v0
	v_mov_b32_e32 v105, v0
	v_mov_b32_e32 v106, v0
	v_mov_b32_e32 v107, v0
	v_mov_b32_e32 v108, v0
	v_mov_b32_e32 v109, v0
	v_mov_b32_e32 v110, v0
	v_mov_b32_e32 v111, v0
	v_mov_b32_e32 v120, v0
	v_mov_b32_e32 v121, v0
	v_mov_b32_e32 v122, v0
	v_mov_b32_e32 v123, v0
	v_mov_b32_e32 v124, v0
	v_mov_b32_e32 v125, v0
	v_mov_b32_e32 v126, v0
	v_mov_b32_e32 v127, v0
	s_mov_b64 s[58:59], 0x80

; #define LAS __attribute__((address_space(3)))
; __device__ __forceinline__ unsigned cvt_pk_bf16(float lo, float hi) { const f32x2 v = {lo, hi}; const bf16x2_t b = __builtin_convertvector(v, bf16x2_t); return __builtin_bit_cast(unsigned, b); }
; __device__ __forceinline__ float bflo(unsigned w) { return __uint_as_float(w << 16); }
; __device__ __forceinline__ float bfhi(unsigned w) { return __uint_as_float(w & 0xffff0000u); }
; template <bool PASS2>
; __device__ __forceinline__ void gla_pass(LAS unsigned char* lds, const Params& p, int layer) {
;     ...
;             bf16x8 wB1, wB2; float biasx;
;             { const float* Wc = (dir ? p.wdu_b : p.wdu_f) + (size_t)layer * 16 * 512 + h * 128 + wid * 16 + fr;
;               float wv[8]; unsigned h1[4], h2[4];
; #pragma unroll
;               for (int j = 0; j < 8; ++j) wv[j] = Wc[((fq & 1) * 8 + j) * 512];
; #pragma unroll
;               for (int jp = 0; jp < 4; ++jp) { const float a = wv[2 * jp], bq = wv[2 * jp + 1]; const unsigned hi = cvt_pk_bf16(a, bq);
;                   const unsigned lo = cvt_pk_bf16(a - bflo(hi), bq - bfhi(hi)); h1[jp] = hi; h2[jp] = fq < 2 ? lo : 0u; }
;               wB1 = __builtin_bit_cast(bf16x8, (u32x4){h1[0], h1[1], h1[2], h1[3]}); wB2 = __builtin_bit_cast(bf16x8, (u32x4){h2[0], h2[1], h2[2], h2[3]});
;               biasx = (dir ? p.bd_b : p.bd_f)[layer * 512 + h * 128 + wid * 16 + fr]; }
;             f32x4 accS[8][2];
; #pragma unroll
;             for (int m8 = 0; m8 < 8; ++m8)
; #pragma unroll
;                 for (int n = 0; n < 2; ++n) accS[m8][n] = (f32x4){0.f, 0.f, 0.f, 0.f};
;             float gtot0 = 0.f, gtot1 = 0.f;
;             u32x4 rk[2], rq[2], rv[4]; u32x4 rl = (u32x4){0u, 0u, 0u, 0u};
;     ...
;             GLA_ISSUE(0);
;     ...
;                 if (tid < 256) { const int row = tid >> 2, seg = tid & 3; *(LAS u32x4*)(lds + SLR + row * 64 + seg * 16) = rl; }
.LBB0_450:
	s_or_b64 exec, exec, s[4:5]
	s_waitcnt vmcnt(0)
	s_and_saveexec_b64 s[4:5], s[12:13]
	ds_write_b128 v211, v[8:11]
	s_or_b64 exec, exec, s[4:5]
	s_waitcnt lgkmcnt(0)
	s_barrier
	v_cvt_pk_bf16_f32 v12, v16, v17
	v_lshlrev_b32_e32 v24, 16, v12
	v_and_b32_e32 v25, 0xffff0000, v12
	v_pk_add_f32 v[16:17], v[16:17], v[24:25] neg_lo:[0,1] neg_hi:[0,1]
	v_readlane_b32 s4, v254, 43
	v_cvt_pk_bf16_f32 v13, v16, v17
	v_cndmask_b32_e64 v16, 0, v13, s[10:11]
	s_waitcnt vmcnt(5)
	v_cvt_pk_bf16_f32 v13, v14, v15
	v_lshlrev_b32_e32 v24, 16, v13
	v_and_b32_e32 v25, 0xffff0000, v13
	v_pk_add_f32 v[14:15], v[14:15], v[24:25] neg_lo:[0,1] neg_hi:[0,1]
	v_readlane_b32 s5, v254, 44
	v_cvt_pk_bf16_f32 v14, v14, v15
	v_cndmask_b32_e64 v17, 0, v14, s[10:11]
	v_cvt_pk_bf16_f32 v14, v18, v19
	v_lshlrev_b32_e32 v24, 16, v14
	v_and_b32_e32 v25, 0xffff0000, v14
	v_pk_add_f32 v[18:19], v[18:19], v[24:25] neg_lo:[0,1] neg_hi:[0,1]
	v_mov_b32_e32 v162, 0
	v_cvt_pk_bf16_f32 v15, v18, v19
	v_cndmask_b32_e64 v18, 0, v15, s[10:11]
	s_waitcnt vmcnt(3)
	v_cvt_pk_bf16_f32 v15, v20, v21
	v_lshlrev_b32_e32 v24, 16, v15
	v_and_b32_e32 v25, 0xffff0000, v15
	v_pk_add_f32 v[20:21], v[20:21], v[24:25] neg_lo:[0,1] neg_hi:[0,1]
	s_xor_b64 s[86:87], s[14:15], -1
	v_cvt_pk_bf16_f32 v19, v20, v21
	v_cndmask_b32_e64 v20, 0, 1, s[4:5]
	v_readlane_b32 s4, v254, 41
	v_readlane_b32 s5, v254, 42
	s_mov_b32 s68, 0
	v_cndmask_b32_e64 v19, 0, v19, s[10:11]
	v_cndmask_b32_e64 v21, 0, 1, s[4:5]
	v_cndmask_b32_e64 v20, v20, v21, s[14:15]
	v_readlane_b32 s4, v254, 47
	v_and_b32_e32 v20, 1, v20
	v_readlane_b32 s5, v254, 48
	v_cmp_eq_u32_e64 s[34:35], 1, v20
	v_lshl_add_u64 v[164:165], v[22:23], 1, v[128:129]
	v_cndmask_b32_e64 v20, 0, 1, s[4:5]
	v_readlane_b32 s4, v254, 45
	v_readlane_b32 s5, v254, 46
	s_xor_b64 s[50:51], s[16:17], s[14:15]
	s_xor_b64 s[52:53], s[18:19], s[14:15]
	v_cndmask_b32_e64 v21, 0, 1, s[4:5]
	v_cndmask_b32_e64 v20, v20, v21, s[14:15]
	v_readlane_b32 s4, v254, 51
	v_and_b32_e32 v20, 1, v20
	v_readlane_b32 s5, v254, 52
	v_cmp_eq_u32_e64 s[36:37], 1, v20
	s_xor_b64 s[54:55], s[20:21], s[14:15]
	v_cndmask_b32_e64 v20, 0, 1, s[4:5]
	v_readlane_b32 s4, v254, 49
	v_readlane_b32 s5, v254, 50
	s_xor_b64 s[56:57], s[22:23], s[14:15]
	s_xor_b64 s[58:59], s[24:25], s[14:15]
	v_cndmask_b32_e64 v21, 0, 1, s[4:5]
	v_cndmask_b32_e64 v20, v20, v21, s[14:15]
	v_readlane_b32 s4, v254, 55
	v_and_b32_e32 v20, 1, v20
	v_readlane_b32 s5, v254, 56
	v_cmp_eq_u32_e64 s[38:39], 1, v20
	s_xor_b64 s[60:61], s[26:27], s[14:15]
	v_cndmask_b32_e64 v20, 0, 1, s[4:5]
	v_readlane_b32 s4, v254, 53
	v_readlane_b32 s5, v254, 54
	s_xor_b64 s[62:63], s[28:29], s[14:15]
	s_xor_b64 s[64:65], s[30:31], s[14:15]
	v_cndmask_b32_e64 v21, 0, 1, s[4:5]
	v_cndmask_b32_e64 v20, v20, v21, s[14:15]
	v_readlane_b32 s4, v254, 59
	v_and_b32_e32 v20, 1, v20
	v_readlane_b32 s5, v254, 60
	v_cmp_eq_u32_e64 s[40:41], 1, v20
	v_mov_b32_e32 v163, 0
	v_cndmask_b32_e64 v20, 0, 1, s[4:5]
	v_readlane_b32 s4, v254, 57
	v_readlane_b32 s5, v254, 58
	v_mov_b32_e32 v22, v162
	v_mov_b32_e32 v23, v162
	v_cndmask_b32_e64 v21, 0, 1, s[4:5]
	v_cndmask_b32_e64 v20, v20, v21, s[14:15]
	v_readlane_b32 s4, v254, 63
	v_and_b32_e32 v20, 1, v20
	v_readlane_b32 s5, v255, 0
	v_cmp_eq_u32_e64 s[42:43], 1, v20
	v_mov_b32_e32 v40, 0
	v_cndmask_b32_e64 v20, 0, 1, s[4:5]
	v_readlane_b32 s4, v254, 61
	v_readlane_b32 s5, v254, 62
	v_mov_b32_e32 v41, v162
	v_mov_b32_e32 v42, v162
	v_cndmask_b32_e64 v21, 0, 1, s[4:5]
	v_cndmask_b32_e64 v20, v20, v21, s[14:15]
	v_readlane_b32 s4, v255, 3
	v_and_b32_e32 v20, 1, v20
	v_readlane_b32 s5, v255, 4
	v_cmp_eq_u32_e64 s[44:45], 1, v20
	v_mov_b32_e32 v43, v162
	v_cndmask_b32_e64 v20, 0, 1, s[4:5]
	v_readlane_b32 s4, v255, 1
	v_readlane_b32 s5, v255, 2
	v_mov_b32_e32 v52, 0
	v_mov_b32_e32 v53, v162
	v_cndmask_b32_e64 v21, 0, 1, s[4:5]
	v_cndmask_b32_e64 v20, v20, v21, s[14:15]
	v_and_b32_e32 v20, 1, v20
	v_cmp_eq_u32_e64 s[46:47], 1, v20
	v_cndmask_b32_e64 v20, 0, 1, s[74:75]
	v_cndmask_b32_e64 v21, 0, 1, s[6:7]
	v_cndmask_b32_e64 v20, v20, v21, s[14:15]
	v_and_b32_e32 v20, 1, v20
	v_cmp_eq_u32_e64 s[48:49], 1, v20
	v_mov_b32_e32 v20, 0
	v_mov_b32_e32 v21, v162
	v_mov_b32_e32 v54, v162
	v_mov_b32_e32 v55, v162
	v_mov_b32_e32 v64, 0
	v_mov_b32_e32 v65, v162
	v_mov_b32_e32 v66, v162
	v_mov_b32_e32 v67, v162
	v_mov_b32_e32 v44, 0
	v_mov_b32_e32 v45, v162
	v_mov_b32_e32 v46, v162
	v_mov_b32_e32 v47, v162
	v_mov_b32_e32 v48, 0
	v_mov_b32_e32 v49, v162
	v_mov_b32_e32 v50, v162
	v_mov_b32_e32 v51, v162
	v_mov_b32_e32 v68, 0
	v_mov_b32_e32 v69, v162
	v_mov_b32_e32 v70, v162
	v_mov_b32_e32 v71, v162
	v_mov_b32_e32 v72, 0
	v_mov_b32_e32 v73, v162
	v_mov_b32_e32 v74, v162
	v_mov_b32_e32 v75, v162
	v_mov_b32_e32 v56, 0
	v_mov_b32_e32 v57, v162
	v_mov_b32_e32 v58, v162
	v_mov_b32_e32 v59, v162
	v_mov_b32_e32 v60, 0
	v_mov_b32_e32 v61, v162
	v_mov_b32_e32 v62, v162
	v_mov_b32_e32 v63, v162
	v_mov_b32_e32 v32, 0
	v_mov_b32_e32 v33, v162
	v_mov_b32_e32 v34, v162
	v_mov_b32_e32 v35, v162
	v_mov_b32_e32 v36, 0
	v_mov_b32_e32 v37, v162
	v_mov_b32_e32 v38, v162
	v_mov_b32_e32 v39, v162
	v_mov_b32_e32 v24, 0
	v_mov_b32_e32 v25, v162
	v_mov_b32_e32 v26, v162
	v_mov_b32_e32 v27, v162
	v_mov_b32_e32 v28, 0
	v_mov_b32_e32 v29, v162
	v_mov_b32_e32 v30, v162
	v_mov_b32_e32 v31, v162
	v_mov_b32_e32 v76, 0
	v_mov_b32_e32 v77, v162
	v_mov_b32_e32 v78, v162
	v_mov_b32_e32 v79, v162
	v_mov_b32_e32 v80, 0
	v_mov_b32_e32 v81, v162
	v_mov_b32_e32 v82, v162
	v_mov_b32_e32 v83, v162
	s_branch .LBB0_453

; #define LAS __attribute__((address_space(3)))
; template <bool PASS2>
; __device__ __forceinline__ void gla_pass(LAS unsigned char* lds, const Params& p, int layer) {
;     ...
;             GLA_ISSUE(0);
; #pragma unroll 1
;             for (int cc = 0; cc < 8; ++cc) {
;                 const int chunk = dir ? 7 - cc : cc;
;                 const int t0 = b * SEQL + grp * 512 + chunk * 64;
; #pragma unroll
;                 for (int it = 0; it < 2; ++it) { const int pi = tid + 512 * it, row = pi >> 4, seg = pi & 15;
;                     *(LAS u32x4*)(lds + SK + row * 272 + seg * 16) = rk[it];
;                     if (PASS2) rq[it] = *(const u32x4*)(P + (size_t)(t0 + row) * PW + h * 128 + seg * 8); }
; #pragma unroll
;                 for (int it = 0; it < 4; ++it) { const int pi = tid + 512 * it, row = pi >> 5, seg = pi & 31;
;                     rv[it] = *(const u32x4*)(P + (size_t)(t0 + row) * PW + 1024 + h * 256 + seg * 8); }
;                 if (tid < 256) { const int row = tid >> 2, seg = tid & 3; *(LAS u32x4*)(lds + SLR + row * 64 + seg * 16) = rl; }
;                 __syncthreads();
; #pragma unroll 1
;                 for (int m = 0; m < 4; ++m) {
;                     const bf16x8 A = *(LAS bf16x8*)(lds + SLR + (m * 16 + fr) * 64 + fq * 16);
;                     f32x4 xx = (f32x4){0.f, 0.f, 0.f, 0.f};
;                     xx = MFMA16(A, wB1, xx); xx = MFMA16(A, wB2, xx);
; #pragma unroll
;                     for (int jj = 0; jj < 4; ++jj) { const float x = xx[jj] + biasx; const float ls = fminf(x, 0.f) - __logf(1.f + __expf(-fabsf(x)));
;                         *(LAS float*)(lds + SX + ((m * 16 + 4 * fq + jj) * 132 + wid * 16 + fr) * 4) = ls * 0.0625f; }
;                 }
;                 if (PASS2) {
; #pragma unroll
;                     for (int it = 0; it < 2; ++it) { const int pi = tid + 512 * it, row = pi >> 4, seg = pi & 15; *(LAS u32x4*)(lds + SQ + row * 272 + seg * 16) = rq[it]; } }
;                 __syncthreads();
;                 float c0[8], c1[8];
; #pragma unroll
;                 for (int e = 0; e < 8; ++e) { const f32x2 t2 = *(LAS f32x2*)(lds + SX + ((wid * 8 + e) * 132 + dk0) * 4); c0[e] = t2.x; c1[e] = t2.y; }
;                 if (dir == 0) {
; #pragma unroll
;                     for (int e = 1; e < 8; ++e) { c0[e] += c0[e - 1]; c1[e] += c1[e - 1]; }
;                 } else {
; #pragma unroll
.LBB0_453:
	s_sub_i32 s66, 7, s68
	s_and_b64 s[4:5], s[14:15], exec
	s_cselect_b32 s4, s68, s66
	s_lshl_b32 s69, s4, 6
	s_add_i32 s69, s69, s97
	v_add_u32_e32 v108, v184, v191
	s_waitcnt vmcnt(6)
	ds_write_b128 v108, v[0:3] offset:17408
	v_add_u32_e32 v108, v184, v192
	s_waitcnt vmcnt(6)
	ds_write_b128 v108, v[4:7] offset:17408
	s_sub_i32 s66, 6, s68
	s_add_i32 s4, s68, 1
	s_and_b64 vcc, s[14:15], exec
	s_cselect_b32 s4, s4, s66
	s_lshl_b32 s66, s4, 6
	s_add_i32 s66, s66, s97
	v_add_u32_e32 v0, s66, v189
	v_add_u32_e32 v2, s66, v190
	v_mad_i64_i32 v[0:1], s[4:5], v0, s80, v[140:141]
	v_mad_i64_i32 v[4:5], s[4:5], v2, s80, v[140:141]
	global_load_dwordx4 v[0:3], v[0:1], off offset:1024
	s_nop 0
	global_load_dwordx4 v[4:7], v[4:5], off offset:1024
	s_and_saveexec_b64 s[4:5], s[12:13]
	s_cbranch_execz .Lgla_t3_skip
	v_add_u32_e32 v8, s66, v188
	v_ashrrev_i32_e32 v9, 31, v8
	v_lshlrev_b64 v[8:9], 7, v[8:9]
	v_lshl_add_u64 v[8:9], v[164:165], 0, v[8:9]
	global_load_dwordx4 v[8:11], v[8:9], off
.Lgla_t3_skip:
	s_or_b64 exec, exec, s[4:5]
	s_mov_b32 s4, 4
	v_mov_b32_e32 v108, v210
	v_mov_b32_e32 v109, v209
	v_mov_b32_e32 v110, v208
.LBB0_456:
	v_add_u32_e32 v111, 0, v110
	ds_read_b128 v[112:115], v111
	s_add_i32 s4, s4, -1
	v_add_u32_e32 v110, 0x400, v110
	s_cmp_lg_u32 s4, 0
	s_waitcnt lgkmcnt(0)
	v_mfma_f32_16x16x32_bf16 v[166:169], v[112:115], v[12:15], 0
	v_mfma_f32_16x16x32_bf16 v[112:115], v[112:115], v[16:19], v[166:169]
	s_nop 7
	v_add_f32_e32 v111, v135, v112
	v_min_f32_e32 v112, 0, v111
	v_mul_f32_e64 v111, |v111|, s79
	v_exp_f32_e32 v111, v111
	s_nop 0
	v_add_f32_e32 v111, 1.0, v111
	v_cmp_gt_f32_e32 vcc, s33, v111
	s_nop 1
	v_cndmask_b32_e64 v137, 0, 32, vcc
	v_ldexp_f32 v111, v111, v137
	v_log_f32_e32 v111, v111
	s_nop 0
	v_mul_f32_e32 v137, 0x3f317217, v111
	v_fma_f32 v137, v111, s81, -v137
	v_fmac_f32_e32 v137, 0x3377d1cf, v111
	v_fmac_f32_e32 v137, 0x3f317217, v111
	v_cmp_lt_f32_e64 s[66:67], |v111|, s90
	s_nop 1
	v_cndmask_b32_e64 v111, v111, v137, s[66:67]
	v_cndmask_b32_e32 v137, 0, v225, vcc
	v_sub_f32_e32 v111, v111, v137
	v_sub_f32_e32 v111, v112, v111
	v_mul_f32_e32 v111, 0x3d800000, v111
	v_add_u32_e32 v112, 0, v109
	ds_write_b32 v112, v111
	v_add_f32_e32 v111, v135, v113
	v_min_f32_e32 v112, 0, v111
	v_mul_f32_e64 v111, |v111|, s79
	v_exp_f32_e32 v111, v111
	v_add_u32_e32 v109, 0x2100, v109
	v_add_f32_e32 v111, 1.0, v111
	v_cmp_gt_f32_e32 vcc, s33, v111
	s_nop 1
	v_cndmask_b32_e64 v113, 0, 32, vcc
	v_ldexp_f32 v111, v111, v113
	v_log_f32_e32 v111, v111
	s_nop 0
	v_mul_f32_e32 v113, 0x3f317217, v111
	v_fma_f32 v113, v111, s81, -v113
	v_fmac_f32_e32 v113, 0x3377d1cf, v111
	v_fmac_f32_e32 v113, 0x3f317217, v111
	v_cmp_lt_f32_e64 s[66:67], |v111|, s90
	s_nop 1
	v_cndmask_b32_e64 v111, v111, v113, s[66:67]
	v_cndmask_b32_e32 v113, 0, v225, vcc
	v_sub_f32_e32 v111, v111, v113
	v_sub_f32_e32 v111, v112, v111
	v_add_u32_e32 v112, 0, v108
	v_mul_f32_e32 v111, 0x3d800000, v111
	v_add_u32_e32 v113, 0x15010, v112
	ds_write_b32 v113, v111
	v_add_f32_e32 v111, v135, v114
	v_min_f32_e32 v113, 0, v111
	v_mul_f32_e64 v111, |v111|, s79
	v_exp_f32_e32 v111, v111
	v_add_u32_e32 v108, 0x2100, v108
	v_add_f32_e32 v111, 1.0, v111
	v_cmp_gt_f32_e32 vcc, s33, v111
	s_nop 1
	v_cndmask_b32_e64 v114, 0, 32, vcc
	v_ldexp_f32 v111, v111, v114
	v_log_f32_e32 v111, v111
	s_nop 0
	v_mul_f32_e32 v114, 0x3f317217, v111
	v_fma_f32 v114, v111, s81, -v114
	v_fmac_f32_e32 v114, 0x3377d1cf, v111
	v_fmac_f32_e32 v114, 0x3f317217, v111
	v_cmp_lt_f32_e64 s[66:67], |v111|, s90
	s_nop 1
	v_cndmask_b32_e64 v111, v111, v114, s[66:67]
	v_cndmask_b32_e32 v114, 0, v225, vcc
	v_sub_f32_e32 v111, v111, v114
	v_sub_f32_e32 v111, v113, v111
	v_mul_f32_e32 v111, 0x3d800000, v111
	v_add_u32_e32 v113, 0x15220, v112
	ds_write_b32 v113, v111
	v_add_f32_e32 v111, v135, v115
	v_min_f32_e32 v113, 0, v111
	v_mul_f32_e64 v111, |v111|, s79
	v_exp_f32_e32 v111, v111
	v_add_u32_e32 v112, 0x15430, v112
	v_add_f32_e32 v111, 1.0, v111
	v_cmp_gt_f32_e32 vcc, s33, v111
	s_nop 1
	v_cndmask_b32_e64 v114, 0, 32, vcc
	v_ldexp_f32 v111, v111, v114
	v_log_f32_e32 v111, v111
	s_nop 0
	v_mul_f32_e32 v114, 0x3f317217, v111
	v_fma_f32 v114, v111, s81, -v114
	v_fmac_f32_e32 v114, 0x3377d1cf, v111
	v_fmac_f32_e32 v114, 0x3f317217, v111
	v_cmp_lt_f32_e64 s[66:67], |v111|, s90
	s_nop 1
	v_cndmask_b32_e64 v111, v111, v114, s[66:67]
	v_cndmask_b32_e32 v114, 0, v225, vcc
	v_sub_f32_e32 v111, v111, v114
	v_sub_f32_e32 v111, v113, v111
	v_mul_f32_e32 v111, 0x3d800000, v111
	ds_write_b32 v112, v111
	s_cbranch_scc1 .LBB0_456
	v_add_u32_e32 v108, v185, v191
	s_waitcnt vmcnt(7)
	ds_write_b128 v108, v[104:107]
	v_add_u32_e32 v104, v185, v192
	s_waitcnt vmcnt(6)
	ds_write_b128 v104, v[100:103]
	s_waitcnt lgkmcnt(0)
	s_barrier
	ds_read_b64 v[100:101], v197
	ds_read_b64 v[102:103], v198
	ds_read_b64 v[104:105], v199
	ds_read_b64 v[106:107], v200
	ds_read_b64 v[108:109], v201
	ds_read_b64 v[110:111], v202
	ds_read_b64 v[112:113], v203
	ds_read_b64 v[166:167], v204
	v_cndmask_b32_e64 v114, 0, 1, s[86:87]
	v_cmp_ne_u32_e64 s[66:67], 1, v114
	s_andn2_b64 vcc, exec, s[86:87]
	s_mov_b64 s[4:5], -1
	s_cbranch_vccnz .LBB0_459
	s_waitcnt lgkmcnt(0)
	v_pk_add_f32 v[168:169], v[112:113], v[166:167]
	s_mov_b64 s[4:5], 0
	v_pk_add_f32 v[170:171], v[110:111], v[168:169]
	s_nop 0
	v_pk_add_f32 v[172:173], v[108:109], v[170:171]
	s_nop 0
	v_pk_add_f32 v[174:175], v[106:107], v[172:173]
	s_nop 0
	v_pk_add_f32 v[176:177], v[104:105], v[174:175]
	s_nop 0
	v_pk_add_f32 v[178:179], v[102:103], v[176:177]
	s_nop 0
	v_pk_add_f32 v[180:181], v[100:101], v[178:179]

; #define LAS __attribute__((address_space(3)))
; __device__ __forceinline__ unsigned cvt_pk_bf16(float lo, float hi) { const f32x2 v = {lo, hi}; const bf16x2_t b = __builtin_convertvector(v, bf16x2_t); return __builtin_bit_cast(unsigned, b); }
; __device__ __forceinline__ float bflo(unsigned w) { return __uint_as_float(w << 16); }
; __device__ __forceinline__ float bfhi(unsigned w) { return __uint_as_float(w & 0xffff0000u); }
; template <bool PASS2>
; __device__ __forceinline__ void gla_pass(LAS unsigned char* lds, const Params& p, int layer) {
;     ...
; #pragma unroll
;                 for (int it = 0; it < 4; ++it) { const int pi = tid + 512 * it, row = pi >> 5, seg = pi & 31;
;                     *(LAS u32x4*)(lds + SV + row * 528 + seg * 16) = rv[it]; }
;                 __syncthreads();
;     ...
;                         for (int m = 0; m < 4; ++m) { bf16_t* dst = O + (size_t)(t0 + m * 16 + fr) * 1024 + h * 256 + wid * 32 + n * 16 + 4 * fq; f32x4 v = accO[m];
;                             if (dir) { const u32x2 old = *(const u32x2*)dst; v[0] += bflo(old.x); v[1] += bfhi(old.x); v[2] += bflo(old.y); v[3] += bfhi(old.y); }
;                             *(u32x2*)dst = (u32x2){cvt_pk_bf16(v[0], v[1]), cvt_pk_bf16(v[2], v[3])}; }
.LBB0_495:
	s_waitcnt vmcnt(13)
	ds_write_b128 v212, v[84:87] offset:35840
	s_waitcnt vmcnt(12)
	ds_write_b128 v213, v[88:91] offset:35840
	s_waitcnt vmcnt(11)
	ds_write_b128 v214, v[92:95] offset:35840
	s_waitcnt vmcnt(10)
	ds_write_b128 v215, v[96:99] offset:35840
	s_waitcnt vmcnt(8)
	s_and_saveexec_b64 s[4:5], s[12:13]
	ds_write_b128 v211, v[8:11]
	s_or_b64 exec, exec, s[4:5]
	v_or_b32_e32 v250, s69, v116
	v_mbcnt_lo_u32_b32 v253, -1, 0
	v_ashrrev_i32_e32 v251, 31, v250
	v_mbcnt_hi_u32_b32 v253, -1, v253
	v_lshlrev_b64 v[250:251], 11, v[250:251]
	v_and_b32_e32 v252, 15, v253
	v_lshl_add_u64 v[250:251], v[158:159], 0, v[250:251]
	v_lshrrev_b32_e32 v253, 4, v253
	v_lshlrev_b32_e32 v252, 11, v252
	v_readfirstlane_b32 s4, v250
	v_readfirstlane_b32 s5, v251
	v_lshl_or_b32 v153, v253, 3, v252
	s_and_b64 vcc, exec, s[66:67]
	s_cbranch_vccnz .Lgla_opf_skip
	s_nop 3
	global_load_dwordx2 v[244:245], v153, s[4:5]
	s_add_u32 s4, s4, 0x8000
	s_addc_u32 s5, s5, 0
	global_load_dwordx2 v[246:247], v153, s[4:5]
	s_add_u32 s4, s4, 0x8000
	s_addc_u32 s5, s5, 0
	global_load_dwordx2 v[250:251], v153, s[4:5]
	s_add_u32 s4, s4, 0x8000
	s_addc_u32 s5, s5, 0
	global_load_dwordx2 v[252:253], v153, s[4:5]
	s_sub_u32 s4, s4, 0x18000
	s_subb_u32 s5, s5, 0

; #define LAS __attribute__((address_space(3)))
; __device__ __forceinline__ unsigned cvt_pk_bf16(float lo, float hi) { const f32x2 v = {lo, hi}; const bf16x2_t b = __builtin_convertvector(v, bf16x2_t); return __builtin_bit_cast(unsigned, b); }
; __device__ __forceinline__ float bflo(unsigned w) { return __uint_as_float(w << 16); }
; __device__ __forceinline__ float bfhi(unsigned w) { return __uint_as_float(w & 0xffff0000u); }
; template <bool PASS2>
; __device__ __forceinline__ void gla_pass(LAS unsigned char* lds, const Params& p, int layer) {
;     ...
;                 for (int it = 0; it < 2; ++it) { const int pi = tid + 512 * it, row = pi >> 4, seg = pi & 15;
;                     *(LAS u32x4*)(lds + SK + row * 272 + seg * 16) = rk[it];
;                     if (PASS2) rq[it] = *(const u32x4*)(P + (size_t)(t0 + row) * PW + h * 128 + seg * 8); }
; #pragma unroll
;                 for (int it = 0; it < 4; ++it) { const int pi = tid + 512 * it, row = pi >> 5, seg = pi & 31;
;                     rv[it] = *(const u32x4*)(P + (size_t)(t0 + row) * PW + 1024 + h * 256 + seg * 8); }
;     ...
;                         for (int m = 0; m < 4; ++m) { bf16_t* dst = O + (size_t)(t0 + m * 16 + fr) * 1024 + h * 256 + wid * 32 + n * 16 + 4 * fq; f32x4 v = accO[m];
;                             if (dir) { const u32x2 old = *(const u32x2*)dst; v[0] += bflo(old.x); v[1] += bfhi(old.x); v[2] += bflo(old.y); v[3] += bfhi(old.y); }
;                             *(u32x2*)dst = (u32x2){cvt_pk_bf16(v[0], v[1]), cvt_pk_bf16(v[2], v[3])}; }
;                         asm volatile("" ::: "memory");
;                     }
;                 }
;                 if (cc < 7) GLA_ISSUE(cc + 1);
.Lgla_s4_skip1:
	v_cvt_pk_bf16_f32 v100, v100, v101
	v_cvt_pk_bf16_f32 v101, v102, v103
	global_store_dwordx2 v153, v[100:101], s[4:5] offset:32
	s_add_u32 s4, s4, 0x8000
	s_addc_u32 s5, s5, 0
	v_cvt_pk_bf16_f32 v104, v104, v105
	v_cvt_pk_bf16_f32 v105, v106, v107
	global_store_dwordx2 v153, v[104:105], s[4:5] offset:32
	s_add_u32 s4, s4, 0x8000
	s_addc_u32 s5, s5, 0
	v_cvt_pk_bf16_f32 v108, v108, v109
	v_cvt_pk_bf16_f32 v109, v110, v111
	global_store_dwordx2 v153, v[108:109], s[4:5] offset:32
	s_add_u32 s4, s4, 0x8000
	s_addc_u32 s5, s5, 0
	v_cvt_pk_bf16_f32 v112, v112, v113
	v_cvt_pk_bf16_f32 v113, v114, v115
	global_store_dwordx2 v153, v[112:113], s[4:5] offset:32
	s_cmp_eq_u32 s68, 7
	s_cbranch_scc1 .LBB0_514
	s_sub_i32 s66, 6, s68
	s_add_i32 s68, s68, 1
	s_and_b64 s[4:5], s[14:15], exec
	s_cselect_b32 s4, s68, s66
	s_lshl_b32 s66, s4, 6
	s_add_i32 s66, s66, s97
	v_add_u32_e32 v166, s66, v189
	v_add_u32_e32 v170, s66, v190
	v_mad_i64_i32 v[166:167], s[4:5], v166, s80, v[140:141]
	v_mad_i64_i32 v[170:171], s[4:5], v170, s80, v[140:141]
	global_load_dwordx4 v[104:107], v[166:167], off
	global_load_dwordx4 v[100:103], v[170:171], off
	v_add_u32_e32 v84, s66, v193
	v_add_u32_e32 v86, s66, v194
	v_add_u32_e32 v92, s66, v195
	v_add_u32_e32 v94, s66, v196
	v_mad_i64_i32 v[84:85], s[4:5], v84, s80, v[160:161]
	v_mad_i64_i32 v[88:89], s[4:5], v86, s80, v[160:161]
	v_mad_i64_i32 v[92:93], s[4:5], v92, s80, v[160:161]
	v_mad_i64_i32 v[96:97], s[4:5], v94, s80, v[160:161]
	global_load_dwordx4 v[84:87], v[84:85], off offset:2048
	s_nop 0
	global_load_dwordx4 v[88:91], v[88:89], off offset:2048
	s_nop 0
	global_load_dwordx4 v[92:95], v[92:93], off offset:2048
	s_nop 0
	global_load_dwordx4 v[96:99], v[96:97], off offset:2048
	s_branch .LBB0_452
.Lfar_latch2:
	s_branch .LBB0_2
.LBB0_514:
	s_mov_b32 s68, 8
	s_branch .LBB0_452

;     ...
;         const char* nA = has_next ? (const char*)g.A + (size_t)nxt.pm * tstepA + (size_t)nxt.pn * APN : cA; const char* nB = has_next ? (const char*)g.Bt + (size_t)nxt.pn * tstepB : cB;
;         for (int t = 0; t < nt; t += 2) {
;             const bool last = (t == nt - 2);
;             const char* a1 = cA + (size_t)(t + 1) * kstep;
;             const char* a2 = last ? nA : cA + (size_t)(t + 2) * kstep; const char* b2 = last ? nB : cB + (size_t)(t + 2) * kstep;
;             const char* a3 = a2 + kstep; const char* b3 = b2 + kstep;
;     ...
; #pragma unroll
;         for (int a = 0; a < 2; ++a)
; #pragma unroll
;             for (int b = 0; b < 2; ++b)
; #pragma unroll
;                 for (int m = 0; m < 4; ++m)
; #pragma unroll
;                     for (int n = 0; n < 2; ++n) acc[a][b][m][n] = (f32x4){0.f, 0.f, 0.f, 0.f};
;         cur = nxt; cA = nA; cB = nB; ++ui;
.LBB0_551:
	s_ashr_i32 s21, s20, 31
	s_lshl_b64 s[24:25], s[20:21], 19
	v_readlane_b32 s52, v254, 28
	v_readlane_b32 s53, v254, 29
	s_add_u32 s24, s52, s24
	s_addc_u32 s25, s53, s25
	s_andn2_b64 vcc, exec, s[8:9]
	s_waitcnt lgkmcnt(0)
	s_cbranch_vccnz .Lzskip_7
	s_and_b64 s[12:13], s[12:13], exec
	s_cselect_b32 s21, s25, s29
	s_cselect_b32 s51, s24, s28
	s_add_u32 s12, s28, 0x40080
	s_addc_u32 s13, s29, 0
	s_add_u32 s28, s26, 0x100
	v_mov_b32_e32 v0, 0
	s_addc_u32 s29, s27, 0
	s_mov_b32 s26, 0
	v_mov_b32_e32 v1, v0
	v_mov_b32_e32 v2, v0
	v_mov_b32_e32 v3, v0
	v_mov_b32_e32 v4, v0
	v_mov_b32_e32 v5, v0
	v_mov_b32_e32 v6, v0
	v_mov_b32_e32 v7, v0
	v_mov_b32_e32 v16, v0
	v_mov_b32_e32 v17, v0
	v_mov_b32_e32 v18, v0
	v_mov_b32_e32 v19, v0
	v_mov_b32_e32 v20, v0
	v_mov_b32_e32 v21, v0
	v_mov_b32_e32 v22, v0
	v_mov_b32_e32 v23, v0
	v_mov_b32_e32 v32, v0
	v_mov_b32_e32 v33, v0
	v_mov_b32_e32 v34, v0
	v_mov_b32_e32 v35, v0
	v_mov_b32_e32 v36, v0
	v_mov_b32_e32 v37, v0
	v_mov_b32_e32 v38, v0
	v_mov_b32_e32 v39, v0
	v_mov_b32_e32 v48, v0
	v_mov_b32_e32 v49, v0
	v_mov_b32_e32 v50, v0
	v_mov_b32_e32 v51, v0
	v_mov_b32_e32 v52, v0
	v_mov_b32_e32 v53, v0
	v_mov_b32_e32 v54, v0
	v_mov_b32_e32 v55, v0
	v_mov_b32_e32 v8, v0
	v_mov_b32_e32 v9, v0
	v_mov_b32_e32 v10, v0
	v_mov_b32_e32 v11, v0
	v_mov_b32_e32 v12, v0
	v_mov_b32_e32 v13, v0
	v_mov_b32_e32 v14, v0
	v_mov_b32_e32 v15, v0
	v_mov_b32_e32 v24, v0
	v_mov_b32_e32 v25, v0
	v_mov_b32_e32 v26, v0
	v_mov_b32_e32 v27, v0
	v_mov_b32_e32 v28, v0
	v_mov_b32_e32 v29, v0
	v_mov_b32_e32 v30, v0
	v_mov_b32_e32 v31, v0
	v_mov_b32_e32 v40, v0
	v_mov_b32_e32 v41, v0
	v_mov_b32_e32 v42, v0
	v_mov_b32_e32 v43, v0
	v_mov_b32_e32 v44, v0
	v_mov_b32_e32 v45, v0
	v_mov_b32_e32 v46, v0
	v_mov_b32_e32 v47, v0
	v_mov_b32_e32 v56, v0
	v_mov_b32_e32 v57, v0
	v_mov_b32_e32 v58, v0
	v_mov_b32_e32 v59, v0
	v_mov_b32_e32 v60, v0
	v_mov_b32_e32 v61, v0
	v_mov_b32_e32 v62, v0
	v_mov_b32_e32 v63, v0
	v_mov_b32_e32 v64, v0
	v_mov_b32_e32 v65, v0
	v_mov_b32_e32 v66, v0
	v_mov_b32_e32 v67, v0
	v_mov_b32_e32 v68, v0
	v_mov_b32_e32 v69, v0
	v_mov_b32_e32 v70, v0
	v_mov_b32_e32 v71, v0
	v_mov_b32_e32 v80, v0
	v_mov_b32_e32 v81, v0
	v_mov_b32_e32 v82, v0
	v_mov_b32_e32 v83, v0
	v_mov_b32_e32 v84, v0
	v_mov_b32_e32 v85, v0
	v_mov_b32_e32 v86, v0
	v_mov_b32_e32 v87, v0
	v_mov_b32_e32 v96, v0
	v_mov_b32_e32 v97, v0
	v_mov_b32_e32 v98, v0
	v_mov_b32_e32 v99, v0
	v_mov_b32_e32 v100, v0
	v_mov_b32_e32 v101, v0
	v_mov_b32_e32 v102, v0
	v_mov_b32_e32 v103, v0
	v_mov_b32_e32 v112, v0
	v_mov_b32_e32 v113, v0
	v_mov_b32_e32 v114, v0
	v_mov_b32_e32 v115, v0
	v_mov_b32_e32 v116, v0
	v_mov_b32_e32 v117, v0
	v_mov_b32_e32 v118, v0
	v_mov_b32_e32 v119, v0
	v_mov_b32_e32 v72, v0
	v_mov_b32_e32 v73, v0
	v_mov_b32_e32 v74, v0
	v_mov_b32_e32 v75, v0
	v_mov_b32_e32 v76, v0
	v_mov_b32_e32 v77, v0
	v_mov_b32_e32 v78, v0
	v_mov_b32_e32 v79, v0
	v_mov_b32_e32 v88, v0
	v_mov_b32_e32 v89, v0
	v_mov_b32_e32 v90, v0
	v_mov_b32_e32 v91, v0
	v_mov_b32_e32 v92, v0
	v_mov_b32_e32 v93, v0
	v_mov_b32_e32 v94, v0
	v_mov_b32_e32 v95, v0
	v_mov_b32_e32 v104, v0
	v_mov_b32_e32 v105, v0
	v_mov_b32_e32 v106, v0
	v_mov_b32_e32 v107, v0
	v_mov_b32_e32 v108, v0
	v_mov_b32_e32 v109, v0
	v_mov_b32_e32 v110, v0
	v_mov_b32_e32 v111, v0
	v_mov_b32_e32 v120, v0
	v_mov_b32_e32 v121, v0
	v_mov_b32_e32 v122, v0
	v_mov_b32_e32 v123, v0
	v_mov_b32_e32 v124, v0
	v_mov_b32_e32 v125, v0
	v_mov_b32_e32 v126, v0
	v_mov_b32_e32 v127, v0
	s_mov_b64 s[58:59], 0x80
